# fp8 GEMM epilogues: accumulator-hazard padding right-sized from 48 to 32 wait states (Table 38 needs 12-20)
# speedup vs baseline: 1.0006x; 1.0006x over previous
; DI unsigned pk2(float lo, float hi) { f32x2 v = {lo, hi}; bf16x2v b = __builtin_convertvector(v, bf16x2v); return __builtin_bit_cast(unsigned, b); }
; template <class Epi, class Sched>
; __device__ __forceinline__ void gemm_phase(LAS unsigned char* lds, const Gemm g, const Sched& S, const Epi& E) {
;     ...
;         if constexpr (Epi::FP8) asm volatile("s_nop 15\n\ts_nop 15\n\ts_nop 15" ::: "memory");
;         { int tz = tid; asm volatile("" : "+v"(tz)); const int wz = __builtin_amdgcn_readfirstlane(tz >> 6), lz = tz & 63;
;           E(acc, cur, wz >> 2, wz & 3, lz & 15, lz >> 4); } S.done(cur);
; #pragma unroll
;         for (int j = 0; j < 4; ++j) { const float t = __builtin_amdgcn_exp2f(v[j] * (-0.03125f * 1.44269504088896f));
;             r = __builtin_amdgcn_cvt_pk_u8_f32(fmaxf(frcp(__builtin_fmaf(t, 1.0f / 255.0f, 1.0f / 255.0f)), 1.0f), j, r); }
;         return r; }
;     __device__ __forceinline__ void operator()(const f32x4 (&acc)[2][2][4][2], const Unit& u, int wr, int wc, int fr, int fq) const {
;         if (u.pn >= 12) {
;             const int row0 = u.pm * BM + wr * 64 + fr, col0 = (u.pn - 12) * BM + wc * 32 + 8 * fq;
; #pragma unroll
;             for (int ai = 0; ai < 2; ++ai)
; #pragma unroll
;                 for (int m = 0; m < 4; ++m) { int row = row0 + ai * HALF + m * 16; asm volatile("" : "+v"(row)); bf16_t* rowp = O + (size_t)row * NPROJ + col0;
; #pragma unroll
;                     for (int bj = 0; bj < 2; ++bj) { const f32x4 v0 = acc[ai][bj][m][0] * 0.03125f, v1 = acc[ai][bj][m][1] * 0.03125f;
;                         u32x4 w; w.x = pk2(v0[0], v0[1]); w.y = pk2(v0[2], v0[3]); w.z = pk2(v1[0], v1[1]); w.w = pk2(v1[2], v1[3]);
;                         *(u32x4*)(rowp + bj * HALF) = w; }
;                     asm volatile("" ::: "memory"); }
;             return; }
; #pragma unroll
;         for (int ai = 0; ai < 2; ++ai)
; #pragma unroll
;             for (int m = 0; m < 4; ++m) {
;                 unsigned boff = (unsigned)(((u.pm * 12 + u.pn) * (16 * 512) + ((wr * 4 + wc) * 64 + fq * 16 + fr)) * 8 + ((ai * 4 + m) * 2) * 4096); asm volatile("" : "+v"(boff));
; #pragma unroll
;                 for (int bj = 0; bj < 2; ++bj) { u32x2 w; w.x = q4(acc[ai][bj][m][0]); w.y = q4(acc[ai][bj][m][1]);
;                     *(u32x2*)(G + (boff + bj * 4096)) = w; }
;                 asm volatile("" ::: "memory"); }
.LBB0_331:
	v_mov_b32_e32 v2, v1
	s_nop 15
	s_nop 15
	s_mov_b64 s[26:27], -1
	v_readfirstlane_b32 s29, v2
	s_bfe_u32 s28, s29, 0x20006
	v_and_b32_e32 v4, 15, v2
	v_bfe_u32 v2, v2, 4, 2
	s_cmp_gt_i32 s71, 11
	s_cbranch_scc1 .LBB0_333
	v_mul_f32_e32 v6, 0xbd38aa3b, v144
	v_exp_f32_e32 v6, v6
	v_mul_f32_e32 v7, 0xbd38aa3b, v145
	v_exp_f32_e32 v7, v7
	v_mul_f32_e32 v9, 0xbd38aa3b, v141
	v_fmamk_f32 v6, v6, 0x3b808081, v211
	v_rcp_f32_e32 v6, v6
	v_fmamk_f32 v7, v7, 0x3b808081, v211
	v_rcp_f32_e32 v7, v7
	v_exp_f32_e32 v9, v9
	v_max_f32_e32 v6, 1.0, v6
	v_cvt_pk_u8_f32 v6, v6, 0, 0
	v_max_f32_e32 v7, 1.0, v7
	v_cvt_pk_u8_f32 v6, v7, 1, v6
	v_mul_f32_e32 v7, 0xbd38aa3b, v146
	v_exp_f32_e32 v7, v7
	v_fmamk_f32 v9, v9, 0x3b808081, v211
	v_rcp_f32_e32 v9, v9
	s_mul_i32 s26, s72, 12
	v_fmamk_f32 v7, v7, 0x3b808081, v211
	v_rcp_f32_e32 v7, v7
	v_max_f32_e32 v9, 1.0, v9
	s_and_b32 s27, s29, 0x1fffff00
	s_lshl_b32 s30, s28, 6
	v_max_f32_e32 v7, 1.0, v7
	v_cvt_pk_u8_f32 v6, v7, 2, v6
	v_mul_f32_e32 v7, 0xbd38aa3b, v147
	v_exp_f32_e32 v7, v7
	s_add_i32 s26, s26, s71
	s_or_b32 s27, s30, s27
	v_lshlrev_b32_e32 v5, 4, v2
	v_fmamk_f32 v7, v7, 0x3b808081, v211
	v_rcp_f32_e32 v7, v7
	v_or3_b32 v5, s27, v5, v4
	s_lshl_b32 s26, s26, 16
	v_lshl_add_u32 v5, v5, 3, s26
	v_max_f32_e32 v7, 1.0, v7
	v_cvt_pk_u8_f32 v6, v7, 3, v6
	v_mul_f32_e32 v7, 0xbd38aa3b, v140
	v_exp_f32_e32 v7, v7
	v_mov_b32_e32 v8, v5
	s_mov_b64 s[26:27], 0
	v_fmamk_f32 v7, v7, 0x3b808081, v211
	v_rcp_f32_e32 v7, v7
	s_nop 0
	v_max_f32_e32 v7, 1.0, v7
	v_cvt_pk_u8_f32 v7, v7, 0, 0
	v_cvt_pk_u8_f32 v7, v9, 1, v7
	v_mul_f32_e32 v9, 0xbd38aa3b, v142
	v_exp_f32_e32 v9, v9
	s_nop 0
	v_fmamk_f32 v9, v9, 0x3b808081, v211
	v_rcp_f32_e32 v9, v9
	s_nop 0
	v_max_f32_e32 v9, 1.0, v9
	v_cvt_pk_u8_f32 v7, v9, 2, v7
	v_mul_f32_e32 v9, 0xbd38aa3b, v143
	v_exp_f32_e32 v9, v9
	s_nop 0
	v_fmamk_f32 v9, v9, 0x3b808081, v211
	v_rcp_f32_e32 v9, v9
	s_nop 0
	v_max_f32_e32 v9, 1.0, v9
	v_cvt_pk_u8_f32 v7, v9, 3, v7
	global_store_dwordx2 v8, v[6:7], s[10:11]
	v_mul_f32_e32 v6, 0xbd38aa3b, v136
	v_exp_f32_e32 v6, v6
	v_mul_f32_e32 v7, 0xbd38aa3b, v137
	v_exp_f32_e32 v7, v7
	v_mul_f32_e32 v9, 0xbd38aa3b, v133
	v_fmamk_f32 v6, v6, 0x3b808081, v211
	v_rcp_f32_e32 v6, v6
	v_fmamk_f32 v7, v7, 0x3b808081, v211
	v_rcp_f32_e32 v7, v7
	v_exp_f32_e32 v9, v9
	v_max_f32_e32 v6, 1.0, v6
	v_cvt_pk_u8_f32 v6, v6, 0, 0
	v_max_f32_e32 v7, 1.0, v7
	v_cvt_pk_u8_f32 v6, v7, 1, v6
	v_mul_f32_e32 v7, 0xbd38aa3b, v138
	v_exp_f32_e32 v7, v7
	v_fmamk_f32 v9, v9, 0x3b808081, v211
	v_rcp_f32_e32 v9, v9
	v_add_u32_e32 v8, 0x1000, v8
	v_fmamk_f32 v7, v7, 0x3b808081, v211
	v_rcp_f32_e32 v7, v7
	v_max_f32_e32 v9, 1.0, v9
	v_max_f32_e32 v7, 1.0, v7
	v_cvt_pk_u8_f32 v6, v7, 2, v6
	v_mul_f32_e32 v7, 0xbd38aa3b, v139
	v_exp_f32_e32 v7, v7
	s_nop 0
	v_fmamk_f32 v7, v7, 0x3b808081, v211
	v_rcp_f32_e32 v7, v7
	s_nop 0
	v_max_f32_e32 v7, 1.0, v7
	v_cvt_pk_u8_f32 v6, v7, 3, v6
	v_mul_f32_e32 v7, 0xbd38aa3b, v132
	v_exp_f32_e32 v7, v7
	s_nop 0
	v_fmamk_f32 v7, v7, 0x3b808081, v211
	v_rcp_f32_e32 v7, v7
	s_nop 0
	v_max_f32_e32 v7, 1.0, v7
	v_cvt_pk_u8_f32 v7, v7, 0, 0
	v_cvt_pk_u8_f32 v7, v9, 1, v7
	v_mul_f32_e32 v9, 0xbd38aa3b, v134
	v_exp_f32_e32 v9, v9
	s_nop 0
	v_fmamk_f32 v9, v9, 0x3b808081, v211
	v_rcp_f32_e32 v9, v9
	s_nop 0
	v_max_f32_e32 v9, 1.0, v9
	v_cvt_pk_u8_f32 v7, v9, 2, v7
	v_mul_f32_e32 v9, 0xbd38aa3b, v135
	v_exp_f32_e32 v9, v9
	s_nop 0
	v_fmamk_f32 v9, v9, 0x3b808081, v211
	v_rcp_f32_e32 v9, v9
	s_nop 0
	v_max_f32_e32 v9, 1.0, v9
	v_cvt_pk_u8_f32 v7, v9, 3, v7
	global_store_dwordx2 v8, v[6:7], s[10:11]
	v_mul_f32_e32 v6, 0xbd38aa3b, v128
	v_exp_f32_e32 v6, v6
	v_mul_f32_e32 v7, 0xbd38aa3b, v129
	v_exp_f32_e32 v7, v7
	v_mul_f32_e32 v9, 0xbd38aa3b, v125
	v_fmamk_f32 v6, v6, 0x3b808081, v211
	v_rcp_f32_e32 v6, v6
	v_fmamk_f32 v7, v7, 0x3b808081, v211
	v_rcp_f32_e32 v7, v7
	v_exp_f32_e32 v9, v9
	v_max_f32_e32 v6, 1.0, v6
	v_cvt_pk_u8_f32 v6, v6, 0, 0
	v_max_f32_e32 v7, 1.0, v7
	v_cvt_pk_u8_f32 v6, v7, 1, v6
	v_mul_f32_e32 v7, 0xbd38aa3b, v130
	v_exp_f32_e32 v7, v7
	v_fmamk_f32 v9, v9, 0x3b808081, v211
	v_rcp_f32_e32 v9, v9
	v_add_u32_e32 v8, 0x2000, v5
	v_fmamk_f32 v7, v7, 0x3b808081, v211
	v_rcp_f32_e32 v7, v7
	v_max_f32_e32 v9, 1.0, v9
	v_max_f32_e32 v7, 1.0, v7
	v_cvt_pk_u8_f32 v6, v7, 2, v6
	v_mul_f32_e32 v7, 0xbd38aa3b, v131
	v_exp_f32_e32 v7, v7
	s_nop 0
	v_fmamk_f32 v7, v7, 0x3b808081, v211
	v_rcp_f32_e32 v7, v7
	s_nop 0
	v_max_f32_e32 v7, 1.0, v7
	v_cvt_pk_u8_f32 v6, v7, 3, v6
	v_mul_f32_e32 v7, 0xbd38aa3b, v124
	v_exp_f32_e32 v7, v7
	s_nop 0
	v_fmamk_f32 v7, v7, 0x3b808081, v211
	v_rcp_f32_e32 v7, v7
	s_nop 0
	v_max_f32_e32 v7, 1.0, v7
	v_cvt_pk_u8_f32 v7, v7, 0, 0
	v_cvt_pk_u8_f32 v7, v9, 1, v7
	v_mul_f32_e32 v9, 0xbd38aa3b, v126
	v_exp_f32_e32 v9, v9
	s_nop 0
	v_fmamk_f32 v9, v9, 0x3b808081, v211
	v_rcp_f32_e32 v9, v9
	s_nop 0
	v_max_f32_e32 v9, 1.0, v9
	v_cvt_pk_u8_f32 v7, v9, 2, v7
	v_mul_f32_e32 v9, 0xbd38aa3b, v127
	v_exp_f32_e32 v9, v9
	s_nop 0
	v_fmamk_f32 v9, v9, 0x3b808081, v211
	v_rcp_f32_e32 v9, v9
	s_nop 0
	v_max_f32_e32 v9, 1.0, v9
	v_cvt_pk_u8_f32 v7, v9, 3, v7
	global_store_dwordx2 v8, v[6:7], s[10:11]
	v_mul_f32_e32 v6, 0xbd38aa3b, v120
	v_exp_f32_e32 v6, v6
	v_mul_f32_e32 v7, 0xbd38aa3b, v121
	v_exp_f32_e32 v7, v7
	v_mul_f32_e32 v9, 0xbd38aa3b, v117
	v_fmamk_f32 v6, v6, 0x3b808081, v211
	v_rcp_f32_e32 v6, v6
	v_fmamk_f32 v7, v7, 0x3b808081, v211
	v_rcp_f32_e32 v7, v7
	v_exp_f32_e32 v9, v9
	v_max_f32_e32 v6, 1.0, v6
	v_cvt_pk_u8_f32 v6, v6, 0, 0
	v_max_f32_e32 v7, 1.0, v7
	v_cvt_pk_u8_f32 v6, v7, 1, v6
	v_mul_f32_e32 v7, 0xbd38aa3b, v122
	v_exp_f32_e32 v7, v7
	v_fmamk_f32 v9, v9, 0x3b808081, v211
	v_rcp_f32_e32 v9, v9
; DI unsigned pk2(float lo, float hi) { f32x2 v = {lo, hi}; bf16x2v b = __builtin_convertvector(v, bf16x2v); return __builtin_bit_cast(unsigned, b); }
; DI float frcp(float x) { return __builtin_amdgcn_rcpf(x); }
; #pragma unroll
;         for (int j = 0; j < 4; ++j) { const float t = __builtin_amdgcn_exp2f(v[j] * (-0.03125f * 1.44269504088896f));
;             r = __builtin_amdgcn_cvt_pk_u8_f32(fmaxf(frcp(__builtin_fmaf(t, 1.0f / 255.0f, 1.0f / 255.0f)), 1.0f), j, r); }
;         return r; }
;     __device__ __forceinline__ void operator()(const f32x4 (&acc)[2][2][4][2], const Unit& u, int wr, int wc, int fr, int fq) const {
;         if (u.pn >= 12) {
;             const int row0 = u.pm * BM + wr * 64 + fr, col0 = (u.pn - 12) * BM + wc * 32 + 8 * fq;
; #pragma unroll
;             for (int ai = 0; ai < 2; ++ai)
; #pragma unroll
;                 for (int m = 0; m < 4; ++m) { int row = row0 + ai * HALF + m * 16; asm volatile("" : "+v"(row)); bf16_t* rowp = O + (size_t)row * NPROJ + col0;
; #pragma unroll
;                     for (int bj = 0; bj < 2; ++bj) { const f32x4 v0 = acc[ai][bj][m][0] * 0.03125f, v1 = acc[ai][bj][m][1] * 0.03125f;
;                         u32x4 w; w.x = pk2(v0[0], v0[1]); w.y = pk2(v0[2], v0[3]); w.z = pk2(v1[0], v1[1]); w.w = pk2(v1[2], v1[3]);
;                         *(u32x4*)(rowp + bj * HALF) = w; }
;                     asm volatile("" ::: "memory"); }
;             return; }
; #pragma unroll
;         for (int ai = 0; ai < 2; ++ai)
; #pragma unroll
;             for (int m = 0; m < 4; ++m) {
;                 unsigned boff = (unsigned)(((u.pm * 12 + u.pn) * (16 * 512) + ((wr * 4 + wc) * 64 + fq * 16 + fr)) * 8 + ((ai * 4 + m) * 2) * 4096); asm volatile("" : "+v"(boff));
; #pragma unroll
;                 for (int bj = 0; bj < 2; ++bj) { u32x2 w; w.x = q4(acc[ai][bj][m][0]); w.y = q4(acc[ai][bj][m][1]);
;                     *(u32x2*)(G + (boff + bj * 4096)) = w; }
;                 asm volatile("" ::: "memory"); }
	v_add_u32_e32 v8, 0x1000, v8
	v_fmamk_f32 v7, v7, 0x3b808081, v211
	v_rcp_f32_e32 v7, v7
	v_max_f32_e32 v9, 1.0, v9
	v_max_f32_e32 v7, 1.0, v7
	v_cvt_pk_u8_f32 v6, v7, 2, v6
	v_mul_f32_e32 v7, 0xbd38aa3b, v123
	v_exp_f32_e32 v7, v7
	s_nop 0
	v_fmamk_f32 v7, v7, 0x3b808081, v211
	v_rcp_f32_e32 v7, v7
	s_nop 0
	v_max_f32_e32 v7, 1.0, v7
	v_cvt_pk_u8_f32 v6, v7, 3, v6
	v_mul_f32_e32 v7, 0xbd38aa3b, v116
	v_exp_f32_e32 v7, v7
	s_nop 0
	v_fmamk_f32 v7, v7, 0x3b808081, v211
	v_rcp_f32_e32 v7, v7
	s_nop 0
	v_max_f32_e32 v7, 1.0, v7
	v_cvt_pk_u8_f32 v7, v7, 0, 0
	v_cvt_pk_u8_f32 v7, v9, 1, v7
	v_mul_f32_e32 v9, 0xbd38aa3b, v118
	v_exp_f32_e32 v9, v9
	s_nop 0
	v_fmamk_f32 v9, v9, 0x3b808081, v211
	v_rcp_f32_e32 v9, v9
	s_nop 0
	v_max_f32_e32 v9, 1.0, v9
	v_cvt_pk_u8_f32 v7, v9, 2, v7
	v_mul_f32_e32 v9, 0xbd38aa3b, v119
	v_exp_f32_e32 v9, v9
	s_nop 0
	v_fmamk_f32 v9, v9, 0x3b808081, v211
	v_rcp_f32_e32 v9, v9
	s_nop 0
	v_max_f32_e32 v9, 1.0, v9
	v_cvt_pk_u8_f32 v7, v9, 3, v7
	global_store_dwordx2 v8, v[6:7], s[10:11]
	v_mul_f32_e32 v6, 0xbd38aa3b, v112
	v_exp_f32_e32 v6, v6
	v_mul_f32_e32 v7, 0xbd38aa3b, v113
	v_exp_f32_e32 v7, v7
	v_mul_f32_e32 v9, 0xbd38aa3b, v109
	v_fmamk_f32 v6, v6, 0x3b808081, v211
	v_rcp_f32_e32 v6, v6
	v_fmamk_f32 v7, v7, 0x3b808081, v211
	v_rcp_f32_e32 v7, v7
	v_exp_f32_e32 v9, v9
	v_max_f32_e32 v6, 1.0, v6
	v_cvt_pk_u8_f32 v6, v6, 0, 0
	v_max_f32_e32 v7, 1.0, v7
	v_cvt_pk_u8_f32 v6, v7, 1, v6
	v_mul_f32_e32 v7, 0xbd38aa3b, v114
	v_exp_f32_e32 v7, v7
	v_fmamk_f32 v9, v9, 0x3b808081, v211
	v_rcp_f32_e32 v9, v9
	v_add_u32_e32 v8, 0x4000, v5
	v_fmamk_f32 v7, v7, 0x3b808081, v211
	v_rcp_f32_e32 v7, v7
	v_max_f32_e32 v9, 1.0, v9
	v_max_f32_e32 v7, 1.0, v7
	v_cvt_pk_u8_f32 v6, v7, 2, v6
	v_mul_f32_e32 v7, 0xbd38aa3b, v115
	v_exp_f32_e32 v7, v7
	s_nop 0
	v_fmamk_f32 v7, v7, 0x3b808081, v211
	v_rcp_f32_e32 v7, v7
	s_nop 0
	v_max_f32_e32 v7, 1.0, v7
	v_cvt_pk_u8_f32 v6, v7, 3, v6
	v_mul_f32_e32 v7, 0xbd38aa3b, v108
	v_exp_f32_e32 v7, v7
	s_nop 0
	v_fmamk_f32 v7, v7, 0x3b808081, v211
	v_rcp_f32_e32 v7, v7
	s_nop 0
	v_max_f32_e32 v7, 1.0, v7
	v_cvt_pk_u8_f32 v7, v7, 0, 0
	v_cvt_pk_u8_f32 v7, v9, 1, v7
	v_mul_f32_e32 v9, 0xbd38aa3b, v110
	v_exp_f32_e32 v9, v9
	s_nop 0
	v_fmamk_f32 v9, v9, 0x3b808081, v211
	v_rcp_f32_e32 v9, v9
	s_nop 0
	v_max_f32_e32 v9, 1.0, v9
	v_cvt_pk_u8_f32 v7, v9, 2, v7
	v_mul_f32_e32 v9, 0xbd38aa3b, v111
	v_exp_f32_e32 v9, v9
	s_nop 0
	v_fmamk_f32 v9, v9, 0x3b808081, v211
	v_rcp_f32_e32 v9, v9
	s_nop 0
	v_max_f32_e32 v9, 1.0, v9
	v_cvt_pk_u8_f32 v7, v9, 3, v7
	global_store_dwordx2 v8, v[6:7], s[10:11]
	v_mul_f32_e32 v6, 0xbd38aa3b, v104
	v_exp_f32_e32 v6, v6
	v_mul_f32_e32 v7, 0xbd38aa3b, v105
	v_exp_f32_e32 v7, v7
	v_mul_f32_e32 v9, 0xbd38aa3b, v101
	v_fmamk_f32 v6, v6, 0x3b808081, v211
	v_rcp_f32_e32 v6, v6
	v_fmamk_f32 v7, v7, 0x3b808081, v211
	v_rcp_f32_e32 v7, v7
	v_exp_f32_e32 v9, v9
	v_max_f32_e32 v6, 1.0, v6
	v_cvt_pk_u8_f32 v6, v6, 0, 0
	v_max_f32_e32 v7, 1.0, v7
	v_cvt_pk_u8_f32 v6, v7, 1, v6
	v_mul_f32_e32 v7, 0xbd38aa3b, v106
	v_exp_f32_e32 v7, v7
	v_fmamk_f32 v9, v9, 0x3b808081, v211
	v_rcp_f32_e32 v9, v9
	v_add_u32_e32 v8, 0x1000, v8
	v_fmamk_f32 v7, v7, 0x3b808081, v211
	v_rcp_f32_e32 v7, v7
	v_max_f32_e32 v9, 1.0, v9
	v_max_f32_e32 v7, 1.0, v7
	v_cvt_pk_u8_f32 v6, v7, 2, v6
	v_mul_f32_e32 v7, 0xbd38aa3b, v107
	v_exp_f32_e32 v7, v7
	s_nop 0
	v_fmamk_f32 v7, v7, 0x3b808081, v211
	v_rcp_f32_e32 v7, v7
	s_nop 0
	v_max_f32_e32 v7, 1.0, v7
	v_cvt_pk_u8_f32 v6, v7, 3, v6
	v_mul_f32_e32 v7, 0xbd38aa3b, v100
	v_exp_f32_e32 v7, v7
	s_nop 0
	v_fmamk_f32 v7, v7, 0x3b808081, v211
	v_rcp_f32_e32 v7, v7
	s_nop 0
	v_max_f32_e32 v7, 1.0, v7
	v_cvt_pk_u8_f32 v7, v7, 0, 0
	v_cvt_pk_u8_f32 v7, v9, 1, v7
	v_mul_f32_e32 v9, 0xbd38aa3b, v102
	v_exp_f32_e32 v9, v9
	s_nop 0
	v_fmamk_f32 v9, v9, 0x3b808081, v211
	v_rcp_f32_e32 v9, v9
	s_nop 0
	v_max_f32_e32 v9, 1.0, v9
	v_cvt_pk_u8_f32 v7, v9, 2, v7
	v_mul_f32_e32 v9, 0xbd38aa3b, v103
	v_exp_f32_e32 v9, v9
	s_nop 0
	v_fmamk_f32 v9, v9, 0x3b808081, v211
	v_rcp_f32_e32 v9, v9
	s_nop 0
	v_max_f32_e32 v9, 1.0, v9
	v_cvt_pk_u8_f32 v7, v9, 3, v7
	global_store_dwordx2 v8, v[6:7], s[10:11]
	v_mul_f32_e32 v6, 0xbd38aa3b, v96
	v_exp_f32_e32 v6, v6
	v_mul_f32_e32 v7, 0xbd38aa3b, v97
	v_exp_f32_e32 v7, v7
	v_mul_f32_e32 v9, 0xbd38aa3b, v93
	v_fmamk_f32 v6, v6, 0x3b808081, v211
	v_rcp_f32_e32 v6, v6
	v_fmamk_f32 v7, v7, 0x3b808081, v211
	v_rcp_f32_e32 v7, v7
	v_exp_f32_e32 v9, v9
	v_max_f32_e32 v6, 1.0, v6
	v_cvt_pk_u8_f32 v6, v6, 0, 0
	v_max_f32_e32 v7, 1.0, v7
	v_cvt_pk_u8_f32 v6, v7, 1, v6
	v_mul_f32_e32 v7, 0xbd38aa3b, v98
	v_exp_f32_e32 v7, v7
	v_fmamk_f32 v9, v9, 0x3b808081, v211
	v_rcp_f32_e32 v9, v9
	v_add_u32_e32 v8, 0x6000, v5
	v_fmamk_f32 v7, v7, 0x3b808081, v211
	v_rcp_f32_e32 v7, v7
	v_max_f32_e32 v9, 1.0, v9
	v_max_f32_e32 v7, 1.0, v7
	v_cvt_pk_u8_f32 v6, v7, 2, v6
	v_mul_f32_e32 v7, 0xbd38aa3b, v99
	v_exp_f32_e32 v7, v7
	s_nop 0
	v_fmamk_f32 v7, v7, 0x3b808081, v211
	v_rcp_f32_e32 v7, v7
	s_nop 0
	v_max_f32_e32 v7, 1.0, v7
	v_cvt_pk_u8_f32 v6, v7, 3, v6
	v_mul_f32_e32 v7, 0xbd38aa3b, v92
	v_exp_f32_e32 v7, v7
	s_nop 0
	v_fmamk_f32 v7, v7, 0x3b808081, v211
	v_rcp_f32_e32 v7, v7
	s_nop 0
	v_max_f32_e32 v7, 1.0, v7
	v_cvt_pk_u8_f32 v7, v7, 0, 0
	v_cvt_pk_u8_f32 v7, v9, 1, v7
	v_mul_f32_e32 v9, 0xbd38aa3b, v94
	v_exp_f32_e32 v9, v9
	s_nop 0
	v_fmamk_f32 v9, v9, 0x3b808081, v211
	v_rcp_f32_e32 v9, v9
	s_nop 0
	v_max_f32_e32 v9, 1.0, v9
	v_cvt_pk_u8_f32 v7, v9, 2, v7
	v_mul_f32_e32 v9, 0xbd38aa3b, v95
	v_exp_f32_e32 v9, v9
	s_nop 0
	v_fmamk_f32 v9, v9, 0x3b808081, v211
	v_rcp_f32_e32 v9, v9
	s_nop 0
	v_max_f32_e32 v9, 1.0, v9
	v_cvt_pk_u8_f32 v7, v9, 3, v7
; DI unsigned pk2(float lo, float hi) { f32x2 v = {lo, hi}; bf16x2v b = __builtin_convertvector(v, bf16x2v); return __builtin_bit_cast(unsigned, b); }
; DI float frcp(float x) { return __builtin_amdgcn_rcpf(x); }
; #pragma unroll
;         for (int j = 0; j < 4; ++j) { const float t = __builtin_amdgcn_exp2f(v[j] * (-0.03125f * 1.44269504088896f));
;             r = __builtin_amdgcn_cvt_pk_u8_f32(fmaxf(frcp(__builtin_fmaf(t, 1.0f / 255.0f, 1.0f / 255.0f)), 1.0f), j, r); }
;         return r; }
;     __device__ __forceinline__ void operator()(const f32x4 (&acc)[2][2][4][2], const Unit& u, int wr, int wc, int fr, int fq) const {
;         if (u.pn >= 12) {
;             const int row0 = u.pm * BM + wr * 64 + fr, col0 = (u.pn - 12) * BM + wc * 32 + 8 * fq;
; #pragma unroll
;             for (int ai = 0; ai < 2; ++ai)
; #pragma unroll
;                 for (int m = 0; m < 4; ++m) { int row = row0 + ai * HALF + m * 16; asm volatile("" : "+v"(row)); bf16_t* rowp = O + (size_t)row * NPROJ + col0;
; #pragma unroll
;                     for (int bj = 0; bj < 2; ++bj) { const f32x4 v0 = acc[ai][bj][m][0] * 0.03125f, v1 = acc[ai][bj][m][1] * 0.03125f;
;                         u32x4 w; w.x = pk2(v0[0], v0[1]); w.y = pk2(v0[2], v0[3]); w.z = pk2(v1[0], v1[1]); w.w = pk2(v1[2], v1[3]);
;                         *(u32x4*)(rowp + bj * HALF) = w; }
;                     asm volatile("" ::: "memory"); }
;             return; }
; #pragma unroll
;         for (int ai = 0; ai < 2; ++ai)
; #pragma unroll
;             for (int m = 0; m < 4; ++m) {
;                 unsigned boff = (unsigned)(((u.pm * 12 + u.pn) * (16 * 512) + ((wr * 4 + wc) * 64 + fq * 16 + fr)) * 8 + ((ai * 4 + m) * 2) * 4096); asm volatile("" : "+v"(boff));
; #pragma unroll
;                 for (int bj = 0; bj < 2; ++bj) { u32x2 w; w.x = q4(acc[ai][bj][m][0]); w.y = q4(acc[ai][bj][m][1]);
;                     *(u32x2*)(G + (boff + bj * 4096)) = w; }
;                 asm volatile("" ::: "memory"); }
	global_store_dwordx2 v8, v[6:7], s[10:11]
	v_mul_f32_e32 v6, 0xbd38aa3b, v88
	v_exp_f32_e32 v6, v6
	v_mul_f32_e32 v7, 0xbd38aa3b, v89
	v_exp_f32_e32 v7, v7
	v_mul_f32_e32 v9, 0xbd38aa3b, v85
	v_fmamk_f32 v6, v6, 0x3b808081, v211
	v_rcp_f32_e32 v6, v6
	v_fmamk_f32 v7, v7, 0x3b808081, v211
	v_rcp_f32_e32 v7, v7
	v_exp_f32_e32 v9, v9
	v_max_f32_e32 v6, 1.0, v6
	v_cvt_pk_u8_f32 v6, v6, 0, 0
	v_max_f32_e32 v7, 1.0, v7
	v_cvt_pk_u8_f32 v6, v7, 1, v6
	v_mul_f32_e32 v7, 0xbd38aa3b, v90
	v_exp_f32_e32 v7, v7
	v_fmamk_f32 v9, v9, 0x3b808081, v211
	v_rcp_f32_e32 v9, v9
	v_add_u32_e32 v8, 0x1000, v8
	v_fmamk_f32 v7, v7, 0x3b808081, v211
	v_rcp_f32_e32 v7, v7
	v_max_f32_e32 v9, 1.0, v9
	v_max_f32_e32 v7, 1.0, v7
	v_cvt_pk_u8_f32 v6, v7, 2, v6
	v_mul_f32_e32 v7, 0xbd38aa3b, v91
	v_exp_f32_e32 v7, v7
	s_nop 0
	v_fmamk_f32 v7, v7, 0x3b808081, v211
	v_rcp_f32_e32 v7, v7
	s_nop 0
	v_max_f32_e32 v7, 1.0, v7
	v_cvt_pk_u8_f32 v6, v7, 3, v6
	v_mul_f32_e32 v7, 0xbd38aa3b, v84
	v_exp_f32_e32 v7, v7
	s_nop 0
	v_fmamk_f32 v7, v7, 0x3b808081, v211
	v_rcp_f32_e32 v7, v7
	s_nop 0
	v_max_f32_e32 v7, 1.0, v7
	v_cvt_pk_u8_f32 v7, v7, 0, 0
	v_cvt_pk_u8_f32 v7, v9, 1, v7
	v_mul_f32_e32 v9, 0xbd38aa3b, v86
	v_exp_f32_e32 v9, v9
	s_nop 0
	v_fmamk_f32 v9, v9, 0x3b808081, v211
	v_rcp_f32_e32 v9, v9
	s_nop 0
	v_max_f32_e32 v9, 1.0, v9
	v_cvt_pk_u8_f32 v7, v9, 2, v7
	v_mul_f32_e32 v9, 0xbd38aa3b, v87
	v_exp_f32_e32 v9, v9
	s_nop 0
	v_fmamk_f32 v9, v9, 0x3b808081, v211
	v_rcp_f32_e32 v9, v9
	s_nop 0
	v_max_f32_e32 v9, 1.0, v9
	v_cvt_pk_u8_f32 v7, v9, 3, v7
	global_store_dwordx2 v8, v[6:7], s[10:11]
	v_mul_f32_e32 v6, 0xbd38aa3b, v80
	v_exp_f32_e32 v6, v6
	v_mul_f32_e32 v7, 0xbd38aa3b, v81
	v_exp_f32_e32 v7, v7
	v_mul_f32_e32 v9, 0xbd38aa3b, v77
	v_fmamk_f32 v6, v6, 0x3b808081, v211
	v_rcp_f32_e32 v6, v6
	v_fmamk_f32 v7, v7, 0x3b808081, v211
	v_rcp_f32_e32 v7, v7
	v_exp_f32_e32 v9, v9
	v_max_f32_e32 v6, 1.0, v6
	v_cvt_pk_u8_f32 v6, v6, 0, 0
	v_max_f32_e32 v7, 1.0, v7
	v_cvt_pk_u8_f32 v6, v7, 1, v6
	v_mul_f32_e32 v7, 0xbd38aa3b, v82
	v_exp_f32_e32 v7, v7
	v_fmamk_f32 v9, v9, 0x3b808081, v211
	v_rcp_f32_e32 v9, v9
	v_add_u32_e32 v8, 0x8000, v5
	v_fmamk_f32 v7, v7, 0x3b808081, v211
	v_rcp_f32_e32 v7, v7
	v_max_f32_e32 v9, 1.0, v9
	v_max_f32_e32 v7, 1.0, v7
	v_cvt_pk_u8_f32 v6, v7, 2, v6
	v_mul_f32_e32 v7, 0xbd38aa3b, v83
	v_exp_f32_e32 v7, v7
	s_nop 0
	v_fmamk_f32 v7, v7, 0x3b808081, v211
	v_rcp_f32_e32 v7, v7
	s_nop 0
	v_max_f32_e32 v7, 1.0, v7
	v_cvt_pk_u8_f32 v6, v7, 3, v6
	v_mul_f32_e32 v7, 0xbd38aa3b, v76
	v_exp_f32_e32 v7, v7
	s_nop 0
	v_fmamk_f32 v7, v7, 0x3b808081, v211
	v_rcp_f32_e32 v7, v7
	s_nop 0
	v_max_f32_e32 v7, 1.0, v7
	v_cvt_pk_u8_f32 v7, v7, 0, 0
	v_cvt_pk_u8_f32 v7, v9, 1, v7
	v_mul_f32_e32 v9, 0xbd38aa3b, v78
	v_exp_f32_e32 v9, v9
	s_nop 0
	v_fmamk_f32 v9, v9, 0x3b808081, v211
	v_rcp_f32_e32 v9, v9
	s_nop 0
	v_max_f32_e32 v9, 1.0, v9
	v_cvt_pk_u8_f32 v7, v9, 2, v7
	v_mul_f32_e32 v9, 0xbd38aa3b, v79
	v_exp_f32_e32 v9, v9
	s_nop 0
	v_fmamk_f32 v9, v9, 0x3b808081, v211
	v_rcp_f32_e32 v9, v9
	s_nop 0
	v_max_f32_e32 v9, 1.0, v9
	v_cvt_pk_u8_f32 v7, v9, 3, v7
	global_store_dwordx2 v8, v[6:7], s[10:11]
	v_mul_f32_e32 v6, 0xbd38aa3b, v72
	v_exp_f32_e32 v6, v6
	v_mul_f32_e32 v7, 0xbd38aa3b, v73
	v_exp_f32_e32 v7, v7
	v_mul_f32_e32 v9, 0xbd38aa3b, v69
	v_fmamk_f32 v6, v6, 0x3b808081, v211
	v_rcp_f32_e32 v6, v6
	v_fmamk_f32 v7, v7, 0x3b808081, v211
	v_rcp_f32_e32 v7, v7
	v_exp_f32_e32 v9, v9
	v_max_f32_e32 v6, 1.0, v6
	v_cvt_pk_u8_f32 v6, v6, 0, 0
	v_max_f32_e32 v7, 1.0, v7
	v_cvt_pk_u8_f32 v6, v7, 1, v6
	v_mul_f32_e32 v7, 0xbd38aa3b, v74
	v_exp_f32_e32 v7, v7
	v_fmamk_f32 v9, v9, 0x3b808081, v211
	v_rcp_f32_e32 v9, v9
	v_add_u32_e32 v8, 0x1000, v8
	v_fmamk_f32 v7, v7, 0x3b808081, v211
	v_rcp_f32_e32 v7, v7
	v_max_f32_e32 v9, 1.0, v9
	v_max_f32_e32 v7, 1.0, v7
	v_cvt_pk_u8_f32 v6, v7, 2, v6
	v_mul_f32_e32 v7, 0xbd38aa3b, v75
	v_exp_f32_e32 v7, v7
	s_nop 0
	v_fmamk_f32 v7, v7, 0x3b808081, v211
	v_rcp_f32_e32 v7, v7
	s_nop 0
	v_max_f32_e32 v7, 1.0, v7
	v_cvt_pk_u8_f32 v6, v7, 3, v6
	v_mul_f32_e32 v7, 0xbd38aa3b, v68
	v_exp_f32_e32 v7, v7
	s_nop 0
	v_fmamk_f32 v7, v7, 0x3b808081, v211
	v_rcp_f32_e32 v7, v7
	s_nop 0
	v_max_f32_e32 v7, 1.0, v7
	v_cvt_pk_u8_f32 v7, v7, 0, 0
	v_cvt_pk_u8_f32 v7, v9, 1, v7
	v_mul_f32_e32 v9, 0xbd38aa3b, v70
	v_exp_f32_e32 v9, v9
	s_nop 0
	v_fmamk_f32 v9, v9, 0x3b808081, v211
	v_rcp_f32_e32 v9, v9
	s_nop 0
	v_max_f32_e32 v9, 1.0, v9
	v_cvt_pk_u8_f32 v7, v9, 2, v7
	v_mul_f32_e32 v9, 0xbd38aa3b, v71
	v_exp_f32_e32 v9, v9
	s_nop 0
	v_fmamk_f32 v9, v9, 0x3b808081, v211
	v_rcp_f32_e32 v9, v9
	s_nop 0
	v_max_f32_e32 v9, 1.0, v9
	v_cvt_pk_u8_f32 v7, v9, 3, v7
	global_store_dwordx2 v8, v[6:7], s[10:11]
	v_mul_f32_e32 v6, 0xbd38aa3b, v64
	v_exp_f32_e32 v6, v6
	v_mul_f32_e32 v7, 0xbd38aa3b, v65
	v_exp_f32_e32 v7, v7
	v_mul_f32_e32 v9, 0xbd38aa3b, v61
	v_fmamk_f32 v6, v6, 0x3b808081, v211
	v_rcp_f32_e32 v6, v6
	v_fmamk_f32 v7, v7, 0x3b808081, v211
	v_rcp_f32_e32 v7, v7
	v_exp_f32_e32 v9, v9
	v_max_f32_e32 v6, 1.0, v6
	v_cvt_pk_u8_f32 v6, v6, 0, 0
	v_max_f32_e32 v7, 1.0, v7
	v_cvt_pk_u8_f32 v6, v7, 1, v6
	v_mul_f32_e32 v7, 0xbd38aa3b, v66
	v_exp_f32_e32 v7, v7
	v_fmamk_f32 v9, v9, 0x3b808081, v211
	v_rcp_f32_e32 v9, v9
	v_add_u32_e32 v8, 0xa000, v5
	v_fmamk_f32 v7, v7, 0x3b808081, v211
	v_rcp_f32_e32 v7, v7
	v_max_f32_e32 v9, 1.0, v9
	v_max_f32_e32 v7, 1.0, v7
	v_cvt_pk_u8_f32 v6, v7, 2, v6
	v_mul_f32_e32 v7, 0xbd38aa3b, v67
	v_exp_f32_e32 v7, v7
	s_nop 0
	v_fmamk_f32 v7, v7, 0x3b808081, v211
	v_rcp_f32_e32 v7, v7
	s_nop 0
	v_max_f32_e32 v7, 1.0, v7
	v_cvt_pk_u8_f32 v6, v7, 3, v6
	v_mul_f32_e32 v7, 0xbd38aa3b, v60
	v_exp_f32_e32 v7, v7
	s_nop 0
; DI unsigned pk2(float lo, float hi) { f32x2 v = {lo, hi}; bf16x2v b = __builtin_convertvector(v, bf16x2v); return __builtin_bit_cast(unsigned, b); }
; DI float frcp(float x) { return __builtin_amdgcn_rcpf(x); }
; #pragma unroll
;         for (int j = 0; j < 4; ++j) { const float t = __builtin_amdgcn_exp2f(v[j] * (-0.03125f * 1.44269504088896f));
;             r = __builtin_amdgcn_cvt_pk_u8_f32(fmaxf(frcp(__builtin_fmaf(t, 1.0f / 255.0f, 1.0f / 255.0f)), 1.0f), j, r); }
;         return r; }
;     __device__ __forceinline__ void operator()(const f32x4 (&acc)[2][2][4][2], const Unit& u, int wr, int wc, int fr, int fq) const {
;         if (u.pn >= 12) {
;             const int row0 = u.pm * BM + wr * 64 + fr, col0 = (u.pn - 12) * BM + wc * 32 + 8 * fq;
; #pragma unroll
;             for (int ai = 0; ai < 2; ++ai)
; #pragma unroll
;                 for (int m = 0; m < 4; ++m) { int row = row0 + ai * HALF + m * 16; asm volatile("" : "+v"(row)); bf16_t* rowp = O + (size_t)row * NPROJ + col0;
; #pragma unroll
;                     for (int bj = 0; bj < 2; ++bj) { const f32x4 v0 = acc[ai][bj][m][0] * 0.03125f, v1 = acc[ai][bj][m][1] * 0.03125f;
;                         u32x4 w; w.x = pk2(v0[0], v0[1]); w.y = pk2(v0[2], v0[3]); w.z = pk2(v1[0], v1[1]); w.w = pk2(v1[2], v1[3]);
;                         *(u32x4*)(rowp + bj * HALF) = w; }
;                     asm volatile("" ::: "memory"); }
;             return; }
; #pragma unroll
;         for (int ai = 0; ai < 2; ++ai)
; #pragma unroll
;             for (int m = 0; m < 4; ++m) {
;                 unsigned boff = (unsigned)(((u.pm * 12 + u.pn) * (16 * 512) + ((wr * 4 + wc) * 64 + fq * 16 + fr)) * 8 + ((ai * 4 + m) * 2) * 4096); asm volatile("" : "+v"(boff));
; #pragma unroll
;                 for (int bj = 0; bj < 2; ++bj) { u32x2 w; w.x = q4(acc[ai][bj][m][0]); w.y = q4(acc[ai][bj][m][1]);
;                     *(u32x2*)(G + (boff + bj * 4096)) = w; }
;                 asm volatile("" ::: "memory"); }
	v_fmamk_f32 v7, v7, 0x3b808081, v211
	v_rcp_f32_e32 v7, v7
	s_nop 0
	v_max_f32_e32 v7, 1.0, v7
	v_cvt_pk_u8_f32 v7, v7, 0, 0
	v_cvt_pk_u8_f32 v7, v9, 1, v7
	v_mul_f32_e32 v9, 0xbd38aa3b, v62
	v_exp_f32_e32 v9, v9
	s_nop 0
	v_fmamk_f32 v9, v9, 0x3b808081, v211
	v_rcp_f32_e32 v9, v9
	s_nop 0
	v_max_f32_e32 v9, 1.0, v9
	v_cvt_pk_u8_f32 v7, v9, 2, v7
	v_mul_f32_e32 v9, 0xbd38aa3b, v63
	v_exp_f32_e32 v9, v9
	s_nop 0
	v_fmamk_f32 v9, v9, 0x3b808081, v211
	v_rcp_f32_e32 v9, v9
	s_nop 0
	v_max_f32_e32 v9, 1.0, v9
	v_cvt_pk_u8_f32 v7, v9, 3, v7
	global_store_dwordx2 v8, v[6:7], s[10:11]
	v_mul_f32_e32 v6, 0xbd38aa3b, v56
	v_exp_f32_e32 v6, v6
	v_mul_f32_e32 v7, 0xbd38aa3b, v57
	v_exp_f32_e32 v7, v7
	v_mul_f32_e32 v9, 0xbd38aa3b, v53
	v_fmamk_f32 v6, v6, 0x3b808081, v211
	v_rcp_f32_e32 v6, v6
	v_fmamk_f32 v7, v7, 0x3b808081, v211
	v_rcp_f32_e32 v7, v7
	v_exp_f32_e32 v9, v9
	v_max_f32_e32 v6, 1.0, v6
	v_cvt_pk_u8_f32 v6, v6, 0, 0
	v_max_f32_e32 v7, 1.0, v7
	v_cvt_pk_u8_f32 v6, v7, 1, v6
	v_mul_f32_e32 v7, 0xbd38aa3b, v58
	v_exp_f32_e32 v7, v7
	v_fmamk_f32 v9, v9, 0x3b808081, v211
	v_rcp_f32_e32 v9, v9
	v_add_u32_e32 v8, 0x1000, v8
	v_fmamk_f32 v7, v7, 0x3b808081, v211
	v_rcp_f32_e32 v7, v7
	v_max_f32_e32 v9, 1.0, v9
	v_max_f32_e32 v7, 1.0, v7
	v_cvt_pk_u8_f32 v6, v7, 2, v6
	v_mul_f32_e32 v7, 0xbd38aa3b, v59
	v_exp_f32_e32 v7, v7
	s_nop 0
	v_fmamk_f32 v7, v7, 0x3b808081, v211
	v_rcp_f32_e32 v7, v7
	s_nop 0
	v_max_f32_e32 v7, 1.0, v7
	v_cvt_pk_u8_f32 v6, v7, 3, v6
	v_mul_f32_e32 v7, 0xbd38aa3b, v52
	v_exp_f32_e32 v7, v7
	s_nop 0
	v_fmamk_f32 v7, v7, 0x3b808081, v211
	v_rcp_f32_e32 v7, v7
	s_nop 0
	v_max_f32_e32 v7, 1.0, v7
	v_cvt_pk_u8_f32 v7, v7, 0, 0
	v_cvt_pk_u8_f32 v7, v9, 1, v7
	v_mul_f32_e32 v9, 0xbd38aa3b, v54
	v_exp_f32_e32 v9, v9
	s_nop 0
	v_fmamk_f32 v9, v9, 0x3b808081, v211
	v_rcp_f32_e32 v9, v9
	s_nop 0
	v_max_f32_e32 v9, 1.0, v9
	v_cvt_pk_u8_f32 v7, v9, 2, v7
	v_mul_f32_e32 v9, 0xbd38aa3b, v55
	v_exp_f32_e32 v9, v9
	s_nop 0
	v_fmamk_f32 v9, v9, 0x3b808081, v211
	v_rcp_f32_e32 v9, v9
	s_nop 0
	v_max_f32_e32 v9, 1.0, v9
	v_cvt_pk_u8_f32 v7, v9, 3, v7
	global_store_dwordx2 v8, v[6:7], s[10:11]
	v_mul_f32_e32 v6, 0xbd38aa3b, v48
	v_exp_f32_e32 v6, v6
	v_mul_f32_e32 v7, 0xbd38aa3b, v49
	v_exp_f32_e32 v7, v7
	v_mul_f32_e32 v9, 0xbd38aa3b, v45
	v_fmamk_f32 v6, v6, 0x3b808081, v211
	v_rcp_f32_e32 v6, v6
	v_fmamk_f32 v7, v7, 0x3b808081, v211
	v_rcp_f32_e32 v7, v7
	v_exp_f32_e32 v9, v9
	v_max_f32_e32 v6, 1.0, v6
	v_cvt_pk_u8_f32 v6, v6, 0, 0
	v_max_f32_e32 v7, 1.0, v7
	v_cvt_pk_u8_f32 v6, v7, 1, v6
	v_mul_f32_e32 v7, 0xbd38aa3b, v50
	v_exp_f32_e32 v7, v7
	v_fmamk_f32 v9, v9, 0x3b808081, v211
	v_rcp_f32_e32 v9, v9
	v_add_u32_e32 v8, 0xc000, v5
	v_fmamk_f32 v7, v7, 0x3b808081, v211
	v_rcp_f32_e32 v7, v7
	v_max_f32_e32 v9, 1.0, v9
	v_max_f32_e32 v7, 1.0, v7
	v_cvt_pk_u8_f32 v6, v7, 2, v6
	v_mul_f32_e32 v7, 0xbd38aa3b, v51
	v_exp_f32_e32 v7, v7
	v_add_u32_e32 v5, 0xe000, v5
	v_fmamk_f32 v7, v7, 0x3b808081, v211
	v_rcp_f32_e32 v7, v7
	s_nop 0
	v_max_f32_e32 v7, 1.0, v7
	v_cvt_pk_u8_f32 v6, v7, 3, v6
	v_mul_f32_e32 v7, 0xbd38aa3b, v44
	v_exp_f32_e32 v7, v7
	s_nop 0
	v_fmamk_f32 v7, v7, 0x3b808081, v211
	v_rcp_f32_e32 v7, v7
	s_nop 0
	v_max_f32_e32 v7, 1.0, v7
	v_cvt_pk_u8_f32 v7, v7, 0, 0
	v_cvt_pk_u8_f32 v7, v9, 1, v7
	v_mul_f32_e32 v9, 0xbd38aa3b, v46
	v_exp_f32_e32 v9, v9
	s_nop 0
	v_fmamk_f32 v9, v9, 0x3b808081, v211
	v_rcp_f32_e32 v9, v9
	s_nop 0
	v_max_f32_e32 v9, 1.0, v9
	v_cvt_pk_u8_f32 v7, v9, 2, v7
	v_mul_f32_e32 v9, 0xbd38aa3b, v47
	v_exp_f32_e32 v9, v9
	s_nop 0
	v_fmamk_f32 v9, v9, 0x3b808081, v211
	v_rcp_f32_e32 v9, v9
	s_nop 0
	v_max_f32_e32 v9, 1.0, v9
	v_cvt_pk_u8_f32 v7, v9, 3, v7
	global_store_dwordx2 v8, v[6:7], s[10:11]
	v_mul_f32_e32 v6, 0xbd38aa3b, v40
	v_exp_f32_e32 v6, v6
	v_mul_f32_e32 v7, 0xbd38aa3b, v41
	v_exp_f32_e32 v7, v7
	v_mul_f32_e32 v9, 0xbd38aa3b, v37
	v_fmamk_f32 v6, v6, 0x3b808081, v211
	v_rcp_f32_e32 v6, v6
	v_fmamk_f32 v7, v7, 0x3b808081, v211
	v_rcp_f32_e32 v7, v7
	v_exp_f32_e32 v9, v9
	v_max_f32_e32 v6, 1.0, v6
	v_cvt_pk_u8_f32 v6, v6, 0, 0
	v_max_f32_e32 v7, 1.0, v7
	v_cvt_pk_u8_f32 v6, v7, 1, v6
	v_mul_f32_e32 v7, 0xbd38aa3b, v42
	v_exp_f32_e32 v7, v7
; DI unsigned pk2(float lo, float hi) { f32x2 v = {lo, hi}; bf16x2v b = __builtin_convertvector(v, bf16x2v); return __builtin_bit_cast(unsigned, b); }
; DI float frcp(float x) { return __builtin_amdgcn_rcpf(x); }
; #pragma unroll
;         for (int j = 0; j < 4; ++j) { const float t = __builtin_amdgcn_exp2f(v[j] * (-0.03125f * 1.44269504088896f));
;             r = __builtin_amdgcn_cvt_pk_u8_f32(fmaxf(frcp(__builtin_fmaf(t, 1.0f / 255.0f, 1.0f / 255.0f)), 1.0f), j, r); }
;         return r; }
;     __device__ __forceinline__ void operator()(const f32x4 (&acc)[2][2][4][2], const Unit& u, int wr, int wc, int fr, int fq) const {
;         if (u.pn >= 12) {
;             const int row0 = u.pm * BM + wr * 64 + fr, col0 = (u.pn - 12) * BM + wc * 32 + 8 * fq;
; #pragma unroll
;             for (int ai = 0; ai < 2; ++ai)
; #pragma unroll
;                 for (int m = 0; m < 4; ++m) { int row = row0 + ai * HALF + m * 16; asm volatile("" : "+v"(row)); bf16_t* rowp = O + (size_t)row * NPROJ + col0;
; #pragma unroll
;                     for (int bj = 0; bj < 2; ++bj) { const f32x4 v0 = acc[ai][bj][m][0] * 0.03125f, v1 = acc[ai][bj][m][1] * 0.03125f;
;                         u32x4 w; w.x = pk2(v0[0], v0[1]); w.y = pk2(v0[2], v0[3]); w.z = pk2(v1[0], v1[1]); w.w = pk2(v1[2], v1[3]);
;                         *(u32x4*)(rowp + bj * HALF) = w; }
;                     asm volatile("" ::: "memory"); }
;             return; }
; #pragma unroll
;         for (int ai = 0; ai < 2; ++ai)
; #pragma unroll
;             for (int m = 0; m < 4; ++m) {
;                 unsigned boff = (unsigned)(((u.pm * 12 + u.pn) * (16 * 512) + ((wr * 4 + wc) * 64 + fq * 16 + fr)) * 8 + ((ai * 4 + m) * 2) * 4096); asm volatile("" : "+v"(boff));
; #pragma unroll
;                 for (int bj = 0; bj < 2; ++bj) { u32x2 w; w.x = q4(acc[ai][bj][m][0]); w.y = q4(acc[ai][bj][m][1]);
;                     *(u32x2*)(G + (boff + bj * 4096)) = w; }
;                 asm volatile("" ::: "memory"); }
	v_fmamk_f32 v9, v9, 0x3b808081, v211
	v_rcp_f32_e32 v9, v9
	v_add_u32_e32 v8, 0x1000, v8
	v_fmamk_f32 v7, v7, 0x3b808081, v211
	v_rcp_f32_e32 v7, v7
	v_max_f32_e32 v9, 1.0, v9
	v_max_f32_e32 v7, 1.0, v7
	v_cvt_pk_u8_f32 v6, v7, 2, v6
	v_mul_f32_e32 v7, 0xbd38aa3b, v43
	v_exp_f32_e32 v7, v7
	s_nop 0
	v_fmamk_f32 v7, v7, 0x3b808081, v211
	v_rcp_f32_e32 v7, v7
	s_nop 0
	v_max_f32_e32 v7, 1.0, v7
	v_cvt_pk_u8_f32 v6, v7, 3, v6
	v_mul_f32_e32 v7, 0xbd38aa3b, v36
	v_exp_f32_e32 v7, v7
	s_nop 0
	v_fmamk_f32 v7, v7, 0x3b808081, v211
	v_rcp_f32_e32 v7, v7
	s_nop 0
	v_max_f32_e32 v7, 1.0, v7
	v_cvt_pk_u8_f32 v7, v7, 0, 0
	v_cvt_pk_u8_f32 v7, v9, 1, v7
	v_mul_f32_e32 v9, 0xbd38aa3b, v38
	v_exp_f32_e32 v9, v9
	s_nop 0
	v_fmamk_f32 v9, v9, 0x3b808081, v211
	v_rcp_f32_e32 v9, v9
	s_nop 0
	v_max_f32_e32 v9, 1.0, v9
	v_cvt_pk_u8_f32 v7, v9, 2, v7
	v_mul_f32_e32 v9, 0xbd38aa3b, v39
	v_exp_f32_e32 v9, v9
	s_nop 0
	v_fmamk_f32 v9, v9, 0x3b808081, v211
	v_rcp_f32_e32 v9, v9
	s_nop 0
	v_max_f32_e32 v9, 1.0, v9
	v_cvt_pk_u8_f32 v7, v9, 3, v7
	global_store_dwordx2 v8, v[6:7], s[10:11]
	v_mul_f32_e32 v6, 0xbd38aa3b, v32
	v_exp_f32_e32 v6, v6
	v_mul_f32_e32 v7, 0xbd38aa3b, v33
	v_exp_f32_e32 v7, v7
	v_mul_f32_e32 v8, 0xbd38aa3b, v29
	v_fmamk_f32 v6, v6, 0x3b808081, v211
	v_rcp_f32_e32 v6, v6
	v_fmamk_f32 v7, v7, 0x3b808081, v211
	v_rcp_f32_e32 v7, v7
	v_exp_f32_e32 v8, v8
	v_max_f32_e32 v6, 1.0, v6
	v_cvt_pk_u8_f32 v6, v6, 0, 0
	v_max_f32_e32 v7, 1.0, v7
	v_cvt_pk_u8_f32 v6, v7, 1, v6
	v_mul_f32_e32 v7, 0xbd38aa3b, v34
	v_exp_f32_e32 v7, v7
	v_fmamk_f32 v8, v8, 0x3b808081, v211
	v_rcp_f32_e32 v8, v8
	v_fmamk_f32 v7, v7, 0x3b808081, v211
	v_rcp_f32_e32 v7, v7
	v_max_f32_e32 v8, 1.0, v8
	v_max_f32_e32 v7, 1.0, v7
	v_cvt_pk_u8_f32 v6, v7, 2, v6
	v_mul_f32_e32 v7, 0xbd38aa3b, v35
	v_exp_f32_e32 v7, v7
	s_nop 0
	v_fmamk_f32 v7, v7, 0x3b808081, v211
	v_rcp_f32_e32 v7, v7
	s_nop 0
	v_max_f32_e32 v7, 1.0, v7
	v_cvt_pk_u8_f32 v6, v7, 3, v6
	v_mul_f32_e32 v7, 0xbd38aa3b, v28
	v_exp_f32_e32 v7, v7
	s_nop 0
	v_fmamk_f32 v7, v7, 0x3b808081, v211
	v_rcp_f32_e32 v7, v7
	s_nop 0
	v_max_f32_e32 v7, 1.0, v7
	v_cvt_pk_u8_f32 v7, v7, 0, 0
	v_cvt_pk_u8_f32 v7, v8, 1, v7
	v_mul_f32_e32 v8, 0xbd38aa3b, v30
	v_exp_f32_e32 v8, v8
	s_nop 0
	v_fmamk_f32 v8, v8, 0x3b808081, v211
	v_rcp_f32_e32 v8, v8
	s_nop 0
	v_max_f32_e32 v8, 1.0, v8
	v_cvt_pk_u8_f32 v7, v8, 2, v7
	v_mul_f32_e32 v8, 0xbd38aa3b, v31
	v_exp_f32_e32 v8, v8
	s_nop 0
	v_fmamk_f32 v8, v8, 0x3b808081, v211
	v_rcp_f32_e32 v8, v8
	s_nop 0
	v_max_f32_e32 v8, 1.0, v8
	v_cvt_pk_u8_f32 v7, v8, 3, v7
	global_store_dwordx2 v5, v[6:7], s[10:11]
	v_mul_f32_e32 v6, 0xbd38aa3b, v24
	v_exp_f32_e32 v6, v6
	v_mul_f32_e32 v7, 0xbd38aa3b, v25
	v_exp_f32_e32 v7, v7
	v_mul_f32_e32 v8, 0xbd38aa3b, v21
	v_fmamk_f32 v6, v6, 0x3b808081, v211
	v_rcp_f32_e32 v6, v6
	v_fmamk_f32 v7, v7, 0x3b808081, v211
	v_rcp_f32_e32 v7, v7
	v_exp_f32_e32 v8, v8
	v_max_f32_e32 v6, 1.0, v6
	v_cvt_pk_u8_f32 v6, v6, 0, 0
	v_max_f32_e32 v7, 1.0, v7
	v_cvt_pk_u8_f32 v6, v7, 1, v6
	v_mul_f32_e32 v7, 0xbd38aa3b, v26
	v_exp_f32_e32 v7, v7
	v_fmamk_f32 v8, v8, 0x3b808081, v211
	v_rcp_f32_e32 v8, v8
	v_add_u32_e32 v5, 0x1000, v5
	v_fmamk_f32 v7, v7, 0x3b808081, v211
	v_rcp_f32_e32 v7, v7
	v_max_f32_e32 v8, 1.0, v8
	v_max_f32_e32 v7, 1.0, v7
	v_cvt_pk_u8_f32 v6, v7, 2, v6
	v_mul_f32_e32 v7, 0xbd38aa3b, v27
	v_exp_f32_e32 v7, v7
	s_nop 0
	v_fmamk_f32 v7, v7, 0x3b808081, v211
	v_rcp_f32_e32 v7, v7
	s_nop 0
	v_max_f32_e32 v7, 1.0, v7
	v_cvt_pk_u8_f32 v6, v7, 3, v6
	v_mul_f32_e32 v7, 0xbd38aa3b, v20
	v_exp_f32_e32 v7, v7
	s_nop 0
	v_fmamk_f32 v7, v7, 0x3b808081, v211
	v_rcp_f32_e32 v7, v7
	s_nop 0
	v_max_f32_e32 v7, 1.0, v7
	v_cvt_pk_u8_f32 v7, v7, 0, 0
	v_cvt_pk_u8_f32 v7, v8, 1, v7
	v_mul_f32_e32 v8, 0xbd38aa3b, v22
	v_exp_f32_e32 v8, v8
	s_nop 0
	v_fmamk_f32 v8, v8, 0x3b808081, v211
	v_rcp_f32_e32 v8, v8
	s_nop 0
	v_max_f32_e32 v8, 1.0, v8
	v_cvt_pk_u8_f32 v7, v8, 2, v7
	v_mul_f32_e32 v8, 0xbd38aa3b, v23
	v_exp_f32_e32 v8, v8
	s_nop 0
	v_fmamk_f32 v8, v8, 0x3b808081, v211
	v_rcp_f32_e32 v8, v8
	s_nop 0
	v_max_f32_e32 v8, 1.0, v8
	v_cvt_pk_u8_f32 v7, v8, 3, v7
	global_store_dwordx2 v5, v[6:7], s[10:11]

; DI unsigned pk2(float lo, float hi) { f32x2 v = {lo, hi}; bf16x2v b = __builtin_convertvector(v, bf16x2v); return __builtin_bit_cast(unsigned, b); }
; DI float bflo(unsigned u) { return __uint_as_float(u << 16); }
; DI float bfhi(unsigned u) { return __uint_as_float(u & 0xffff0000u); }
; template <class Epi, class Sched>
; __device__ __forceinline__ void gemm_phase(LAS unsigned char* lds, const Gemm g, const Sched& S, const Epi& E) {
;     ...
;         if constexpr (Epi::FP8) asm volatile("s_nop 15\n\ts_nop 15\n\ts_nop 15" ::: "memory");
;         { int tz = tid; asm volatile("" : "+v"(tz)); const int wz = __builtin_amdgcn_readfirstlane(tz >> 6), lz = tz & 63;
;           E(acc, cur, wz >> 2, wz & 3, lz & 15, lz >> 4); } S.done(cur);
;     __device__ __forceinline__ void operator()(const f32x4 (&acc)[2][2][4][2], const Unit& u, int wr, int wc, int fr, int fq) const {
;         const int row0 = u.pm * BM + wr * 64 + fr, col0 = u.pn * BM + wc * 32 + 8 * fq;
; #pragma unroll
;         for (int ai = 0; ai < 2; ++ai) {
;             int rowb = row0 + ai * HALF; asm volatile("" : "+v"(rowb)); const size_t off0 = (size_t)rowb * D + col0;
;             u32x4 xr[4][2];
; #pragma unroll
;             for (int m = 0; m < 4; ++m)
; #pragma unroll
;                 for (int bj = 0; bj < 2; ++bj) xr[m][bj] = *(const u32x4*)(XR + off0 + (size_t)(m * 16) * D + bj * HALF);
; #pragma unroll
;             for (int m = 0; m < 4; ++m)
; #pragma unroll
;                 for (int bj = 0; bj < 2; ++bj) { const u32x4 x = xr[m][bj]; const f32x4 v0 = acc[ai][bj][m][0] * (1.0f / 512.0f), v1 = acc[ai][bj][m][1] * (1.0f / 512.0f); u32x4 w;
;                     w.x = pk2(bflo(x.x) * ALPHA + v0[0], bfhi(x.x) * ALPHA + v0[1]); w.y = pk2(bflo(x.y) * ALPHA + v0[2], bfhi(x.y) * ALPHA + v0[3]);
;                     w.z = pk2(bflo(x.z) * ALPHA + v1[0], bfhi(x.z) * ALPHA + v1[1]); w.w = pk2(bflo(x.w) * ALPHA + v1[2], bfhi(x.w) * ALPHA + v1[3]);
;                     *(u32x4*)(H + off0 + (size_t)(m * 16) * D + bj * HALF) = w; }
;             asm volatile("" ::: "memory"); }
;     }
.LBB0_1140:
	v_mov_b32_e32 v4, v1
	s_nop 15
	s_nop 15
	s_lshl_b32 s17, s48, 8
	v_readfirstlane_b32 s16, v4
	s_ashr_i32 s18, s16, 2
	s_andn2_b32 s18, s18, 63
	s_lshr_b32 s16, s16, 1
	s_add_i32 s18, s18, s17
	s_lshl_b32 s17, s47, 8
	s_and_b32 s16, s16, 0x60
	v_and_or_b32 v173, v4, 15, s18
	s_or_b32 s16, s16, s17
	v_lshrrev_b32_e32 v4, 1, v4
	v_and_or_b32 v44, v4, 24, s16
	v_mov_b32_e32 v4, v173
	v_ashrrev_i32_e32 v45, 31, v44
	v_ashrrev_i32_e32 v5, 31, v4
	v_lshlrev_b64 v[4:5], 10, v[4:5]
	v_lshl_add_u64 v[4:5], v[4:5], 0, v[44:45]
	v_lshlrev_b64 v[46:47], 1, v[4:5]
	v_lshl_add_u64 v[4:5], s[10:11], 0, v[46:47]
	global_load_dwordx4 v[24:27], v[4:5], off
	global_load_dwordx4 v[174:177], v[4:5], off offset:256
	v_add_co_u32_e32 v6, vcc, s94, v4
	s_mov_b32 s16, 0x10000
	s_nop 0
	v_addc_co_u32_e32 v7, vcc, 0, v5, vcc
	global_load_dwordx4 v[178:181], v[6:7], off
	global_load_dwordx4 v[20:23], v[6:7], off offset:256
	v_add_co_u32_e32 v6, vcc, s16, v4
	s_mov_b32 s17, 0x18000
	s_nop 0
	v_addc_co_u32_e32 v7, vcc, 0, v5, vcc
	global_load_dwordx4 v[16:19], v[6:7], off
	global_load_dwordx4 v[12:15], v[6:7], off offset:256
	v_add_co_u32_e32 v4, vcc, s17, v4
	s_mov_b32 s18, 0x3fb504f3
	s_nop 0
	v_addc_co_u32_e32 v5, vcc, 0, v5, vcc
	global_load_dwordx4 v[8:11], v[4:5], off
	s_nop 0
	global_load_dwordx4 v[4:7], v[4:5], off offset:256
	v_lshl_add_u64 v[46:47], s[12:13], 0, v[46:47]
	s_mov_b32 s47, s45
	s_mov_b32 s48, s46
	s_waitcnt vmcnt(0)
	v_lshlrev_b32_e32 v182, 16, v24
	v_and_b32_e32 v183, 0xffff0000, v24
	v_pk_fma_f32 v[168:169], v[182:183], s[18:19], v[168:169] op_sel_hi:[1,0,1]
	s_nop 0
	v_cvt_pk_bf16_f32 v24, v168, v169
	v_lshlrev_b32_e32 v168, 16, v25
	v_and_b32_e32 v169, 0xffff0000, v25
	v_pk_fma_f32 v[162:163], v[168:169], s[18:19], v[162:163] op_sel_hi:[1,0,1]
	s_nop 0
	v_cvt_pk_bf16_f32 v25, v162, v163
	v_lshlrev_b32_e32 v162, 16, v26
	v_and_b32_e32 v163, 0xffff0000, v26
	v_pk_fma_f32 v[162:163], v[162:163], s[18:19], v[166:167] op_sel_hi:[1,0,1]
	s_nop 0
	v_cvt_pk_bf16_f32 v26, v162, v163
	v_lshlrev_b32_e32 v162, 16, v27
	v_and_b32_e32 v163, 0xffff0000, v27
	v_pk_fma_f32 v[162:163], v[162:163], s[18:19], v[164:165] op_sel_hi:[1,0,1]
	s_nop 0
	v_cvt_pk_bf16_f32 v27, v162, v163
	global_store_dwordx4 v[46:47], v[24:27], off
	s_nop 1
	v_lshlrev_b32_e32 v24, 16, v174
	v_and_b32_e32 v25, 0xffff0000, v174
	v_lshlrev_b32_e32 v26, 16, v175
	v_and_b32_e32 v27, 0xffff0000, v175
	v_pk_fma_f32 v[24:25], v[24:25], s[18:19], v[160:161] op_sel_hi:[1,0,1]
	v_pk_fma_f32 v[26:27], v[26:27], s[18:19], v[146:147] op_sel_hi:[1,0,1]
	v_cvt_pk_bf16_f32 v24, v24, v25
	v_cvt_pk_bf16_f32 v25, v26, v27
	v_lshlrev_b32_e32 v26, 16, v176
	v_and_b32_e32 v27, 0xffff0000, v176
	v_lshlrev_b32_e32 v146, 16, v177
	v_and_b32_e32 v147, 0xffff0000, v177
	v_pk_fma_f32 v[26:27], v[26:27], s[18:19], v[158:159] op_sel_hi:[1,0,1]
	v_pk_fma_f32 v[144:145], v[146:147], s[18:19], v[144:145] op_sel_hi:[1,0,1]
	v_cvt_pk_bf16_f32 v26, v26, v27
	v_cvt_pk_bf16_f32 v27, v144, v145
	global_store_dwordx4 v[46:47], v[24:27], off offset:256
	s_nop 1
	v_lshlrev_b32_e32 v24, 16, v178
	v_and_b32_e32 v25, 0xffff0000, v178
	v_lshlrev_b32_e32 v26, 16, v179
	v_and_b32_e32 v27, 0xffff0000, v179
	v_pk_fma_f32 v[24:25], v[24:25], s[18:19], v[142:143] op_sel_hi:[1,0,1]
	v_pk_fma_f32 v[26:27], v[26:27], s[18:19], v[138:139] op_sel_hi:[1,0,1]
	v_cvt_pk_bf16_f32 v24, v24, v25
	v_cvt_pk_bf16_f32 v25, v26, v27
	v_lshlrev_b32_e32 v26, 16, v180
	v_and_b32_e32 v27, 0xffff0000, v180
	v_lshlrev_b32_e32 v138, 16, v181
	v_and_b32_e32 v139, 0xffff0000, v181
	v_pk_fma_f32 v[26:27], v[26:27], s[18:19], v[140:141] op_sel_hi:[1,0,1]
	v_pk_fma_f32 v[136:137], v[138:139], s[18:19], v[136:137] op_sel_hi:[1,0,1]
	v_cvt_pk_bf16_f32 v26, v26, v27
	v_cvt_pk_bf16_f32 v27, v136, v137
	v_add_co_u32_e32 v136, vcc, s94, v46
	s_nop 1
	v_addc_co_u32_e32 v137, vcc, 0, v47, vcc
	global_store_dwordx4 v[136:137], v[24:27], off
	s_nop 1
	v_lshlrev_b32_e32 v24, 16, v20
	v_and_b32_e32 v25, 0xffff0000, v20
	v_pk_fma_f32 v[24:25], v[24:25], s[18:19], v[134:135] op_sel_hi:[1,0,1]
	s_nop 0
	v_cvt_pk_bf16_f32 v20, v24, v25
	v_lshlrev_b32_e32 v24, 16, v21
	v_and_b32_e32 v25, 0xffff0000, v21
	v_pk_fma_f32 v[24:25], v[24:25], s[18:19], v[130:131] op_sel_hi:[1,0,1]
	s_nop 0
	v_cvt_pk_bf16_f32 v21, v24, v25
	v_lshlrev_b32_e32 v24, 16, v22
	v_and_b32_e32 v25, 0xffff0000, v22
	v_pk_fma_f32 v[24:25], v[24:25], s[18:19], v[132:133] op_sel_hi:[1,0,1]
	s_nop 0
	v_cvt_pk_bf16_f32 v22, v24, v25
	v_lshlrev_b32_e32 v24, 16, v23
	v_and_b32_e32 v25, 0xffff0000, v23
	v_pk_fma_f32 v[24:25], v[24:25], s[18:19], v[128:129] op_sel_hi:[1,0,1]
	s_nop 0
	v_cvt_pk_bf16_f32 v23, v24, v25
	global_store_dwordx4 v[136:137], v[20:23], off offset:256
	s_nop 1
	v_lshlrev_b32_e32 v20, 16, v16
	v_and_b32_e32 v21, 0xffff0000, v16
	v_pk_fma_f32 v[20:21], v[20:21], s[18:19], v[126:127] op_sel_hi:[1,0,1]
	s_nop 0
	v_cvt_pk_bf16_f32 v16, v20, v21
	v_lshlrev_b32_e32 v20, 16, v17
	v_and_b32_e32 v21, 0xffff0000, v17
	v_pk_fma_f32 v[20:21], v[20:21], s[18:19], v[120:121] op_sel_hi:[1,0,1]
	s_nop 0
	v_cvt_pk_bf16_f32 v17, v20, v21
	v_lshlrev_b32_e32 v20, 16, v18
	v_and_b32_e32 v21, 0xffff0000, v18
	v_pk_fma_f32 v[20:21], v[20:21], s[18:19], v[122:123] op_sel_hi:[1,0,1]
	s_nop 0
	v_cvt_pk_bf16_f32 v18, v20, v21
	v_lshlrev_b32_e32 v20, 16, v19
	v_and_b32_e32 v21, 0xffff0000, v19
	v_pk_fma_f32 v[20:21], v[20:21], s[18:19], v[114:115] op_sel_hi:[1,0,1]
	s_nop 0
	v_cvt_pk_bf16_f32 v19, v20, v21
	v_add_co_u32_e32 v20, vcc, s16, v46
	s_nop 1
	v_addc_co_u32_e32 v21, vcc, 0, v47, vcc
	global_store_dwordx4 v[20:21], v[16:19], off
	s_nop 1
	v_lshlrev_b32_e32 v16, 16, v12
	v_and_b32_e32 v17, 0xffff0000, v12
; DI unsigned pk2(float lo, float hi) { f32x2 v = {lo, hi}; bf16x2v b = __builtin_convertvector(v, bf16x2v); return __builtin_bit_cast(unsigned, b); }
; DI float bflo(unsigned u) { return __uint_as_float(u << 16); }
; DI float bfhi(unsigned u) { return __uint_as_float(u & 0xffff0000u); }
;     __device__ __forceinline__ void operator()(const f32x4 (&acc)[2][2][4][2], const Unit& u, int wr, int wc, int fr, int fq) const {
;         const int row0 = u.pm * BM + wr * 64 + fr, col0 = u.pn * BM + wc * 32 + 8 * fq;
; #pragma unroll
;         for (int ai = 0; ai < 2; ++ai) {
;             int rowb = row0 + ai * HALF; asm volatile("" : "+v"(rowb)); const size_t off0 = (size_t)rowb * D + col0;
;             u32x4 xr[4][2];
; #pragma unroll
;             for (int m = 0; m < 4; ++m)
; #pragma unroll
;                 for (int bj = 0; bj < 2; ++bj) xr[m][bj] = *(const u32x4*)(XR + off0 + (size_t)(m * 16) * D + bj * HALF);
; #pragma unroll
;             for (int m = 0; m < 4; ++m)
; #pragma unroll
;                 for (int bj = 0; bj < 2; ++bj) { const u32x4 x = xr[m][bj]; const f32x4 v0 = acc[ai][bj][m][0] * (1.0f / 512.0f), v1 = acc[ai][bj][m][1] * (1.0f / 512.0f); u32x4 w;
;                     w.x = pk2(bflo(x.x) * ALPHA + v0[0], bfhi(x.x) * ALPHA + v0[1]); w.y = pk2(bflo(x.y) * ALPHA + v0[2], bfhi(x.y) * ALPHA + v0[3]);
;                     w.z = pk2(bflo(x.z) * ALPHA + v1[0], bfhi(x.z) * ALPHA + v1[1]); w.w = pk2(bflo(x.w) * ALPHA + v1[2], bfhi(x.w) * ALPHA + v1[3]);
;                     *(u32x4*)(H + off0 + (size_t)(m * 16) * D + bj * HALF) = w; }
;             asm volatile("" ::: "memory"); }
;     }
	v_pk_fma_f32 v[16:17], v[16:17], s[18:19], v[124:125] op_sel_hi:[1,0,1]
	s_nop 0
	v_cvt_pk_bf16_f32 v12, v16, v17
	v_lshlrev_b32_e32 v16, 16, v13
	v_and_b32_e32 v17, 0xffff0000, v13
	v_pk_fma_f32 v[16:17], v[16:17], s[18:19], v[116:117] op_sel_hi:[1,0,1]
	s_nop 0
	v_cvt_pk_bf16_f32 v13, v16, v17
	v_lshlrev_b32_e32 v16, 16, v14
	v_and_b32_e32 v17, 0xffff0000, v14
	v_pk_fma_f32 v[16:17], v[16:17], s[18:19], v[118:119] op_sel_hi:[1,0,1]
	s_nop 0
	v_cvt_pk_bf16_f32 v14, v16, v17
	v_lshlrev_b32_e32 v16, 16, v15
	v_and_b32_e32 v17, 0xffff0000, v15
	v_pk_fma_f32 v[16:17], v[16:17], s[18:19], v[112:113] op_sel_hi:[1,0,1]
	s_nop 0
	v_cvt_pk_bf16_f32 v15, v16, v17
	global_store_dwordx4 v[20:21], v[12:15], off offset:256
	s_nop 1
	v_lshlrev_b32_e32 v12, 16, v8
	v_and_b32_e32 v13, 0xffff0000, v8
	v_pk_fma_f32 v[12:13], v[12:13], s[18:19], v[110:111] op_sel_hi:[1,0,1]
	s_nop 0
	v_cvt_pk_bf16_f32 v8, v12, v13
	v_lshlrev_b32_e32 v12, 16, v9
	v_and_b32_e32 v13, 0xffff0000, v9
	v_pk_fma_f32 v[12:13], v[12:13], s[18:19], v[104:105] op_sel_hi:[1,0,1]
	s_nop 0
	v_cvt_pk_bf16_f32 v9, v12, v13
	v_lshlrev_b32_e32 v12, 16, v10
	v_and_b32_e32 v13, 0xffff0000, v10
	v_pk_fma_f32 v[12:13], v[12:13], s[18:19], v[106:107] op_sel_hi:[1,0,1]
	s_nop 0
	v_cvt_pk_bf16_f32 v10, v12, v13
	v_lshlrev_b32_e32 v12, 16, v11
	v_and_b32_e32 v13, 0xffff0000, v11
	v_pk_fma_f32 v[12:13], v[12:13], s[18:19], v[98:99] op_sel_hi:[1,0,1]
	s_nop 0
	v_cvt_pk_bf16_f32 v11, v12, v13
	v_add_co_u32_e32 v12, vcc, s17, v46
	s_nop 1
	v_addc_co_u32_e32 v13, vcc, 0, v47, vcc
	global_store_dwordx4 v[12:13], v[8:11], off
	s_nop 1
	v_lshlrev_b32_e32 v8, 16, v4
	v_and_b32_e32 v9, 0xffff0000, v4
	v_pk_fma_f32 v[8:9], v[8:9], s[18:19], v[108:109] op_sel_hi:[1,0,1]
	s_nop 0
	v_cvt_pk_bf16_f32 v4, v8, v9
	v_lshlrev_b32_e32 v8, 16, v5
	v_and_b32_e32 v9, 0xffff0000, v5
	v_pk_fma_f32 v[8:9], v[8:9], s[18:19], v[100:101] op_sel_hi:[1,0,1]
	s_nop 0
	v_cvt_pk_bf16_f32 v5, v8, v9
	v_lshlrev_b32_e32 v8, 16, v6
	v_and_b32_e32 v9, 0xffff0000, v6
	v_pk_fma_f32 v[8:9], v[8:9], s[18:19], v[102:103] op_sel_hi:[1,0,1]
	s_nop 0
	v_cvt_pk_bf16_f32 v6, v8, v9
	v_lshlrev_b32_e32 v8, 16, v7
	v_and_b32_e32 v9, 0xffff0000, v7
	v_pk_fma_f32 v[8:9], v[8:9], s[18:19], v[96:97] op_sel_hi:[1,0,1]
	s_nop 0
	v_cvt_pk_bf16_f32 v7, v8, v9
	global_store_dwordx4 v[12:13], v[4:7], off offset:256
	s_nop 1
	v_add_u32_e32 v4, 0x80, v173
	s_nop 0
	v_ashrrev_i32_e32 v5, 31, v4
	v_lshlrev_b64 v[4:5], 10, v[4:5]
	v_lshl_add_u64 v[4:5], v[4:5], 0, v[44:45]
	v_lshlrev_b64 v[100:101], 1, v[4:5]
	v_lshl_add_u64 v[4:5], s[10:11], 0, v[100:101]
	global_load_dwordx4 v[12:15], v[4:5], off
	global_load_dwordx4 v[16:19], v[4:5], off offset:256
	v_add_co_u32_e32 v6, vcc, s94, v4
	s_waitcnt vmcnt(0)
	v_lshlrev_b32_e32 v102, 16, v12
	v_addc_co_u32_e32 v7, vcc, 0, v5, vcc
	global_load_dwordx4 v[20:23], v[6:7], off
	global_load_dwordx4 v[24:27], v[6:7], off offset:256
	v_add_co_u32_e32 v6, vcc, s16, v4
	v_and_b32_e32 v103, 0xffff0000, v12
	s_nop 0
	v_addc_co_u32_e32 v7, vcc, 0, v5, vcc
	global_load_dwordx4 v[44:47], v[6:7], off
	global_load_dwordx4 v[96:99], v[6:7], off offset:256
	v_add_co_u32_e32 v4, vcc, s17, v4
	v_pk_fma_f32 v[92:93], v[102:103], s[18:19], v[92:93] op_sel_hi:[1,0,1]
	s_nop 0
	v_addc_co_u32_e32 v5, vcc, 0, v5, vcc
	global_load_dwordx4 v[8:11], v[4:5], off
	s_nop 0
	global_load_dwordx4 v[4:7], v[4:5], off offset:256
	v_cvt_pk_bf16_f32 v12, v92, v93
	v_lshlrev_b32_e32 v92, 16, v13
	v_and_b32_e32 v93, 0xffff0000, v13
	v_pk_fma_f32 v[84:85], v[92:93], s[18:19], v[84:85] op_sel_hi:[1,0,1]
	s_nop 0
	v_cvt_pk_bf16_f32 v13, v84, v85
	v_lshlrev_b32_e32 v84, 16, v14
	v_and_b32_e32 v85, 0xffff0000, v14
	v_pk_fma_f32 v[84:85], v[84:85], s[18:19], v[88:89] op_sel_hi:[1,0,1]
	s_nop 0
	v_cvt_pk_bf16_f32 v14, v84, v85
	v_lshlrev_b32_e32 v84, 16, v15
	v_and_b32_e32 v85, 0xffff0000, v15
	v_pk_fma_f32 v[80:81], v[84:85], s[18:19], v[80:81] op_sel_hi:[1,0,1]
	s_nop 0
	v_cvt_pk_bf16_f32 v15, v80, v81
	v_lshl_add_u64 v[80:81], s[12:13], 0, v[100:101]
	global_store_dwordx4 v[80:81], v[12:15], off
	s_nop 1
	v_lshlrev_b32_e32 v12, 16, v16
	v_and_b32_e32 v13, 0xffff0000, v16
	v_lshlrev_b32_e32 v14, 16, v17
	v_and_b32_e32 v15, 0xffff0000, v17
	v_pk_fma_f32 v[12:13], v[12:13], s[18:19], v[94:95] op_sel_hi:[1,0,1]
	v_pk_fma_f32 v[14:15], v[14:15], s[18:19], v[86:87] op_sel_hi:[1,0,1]
	v_cvt_pk_bf16_f32 v12, v12, v13
	v_cvt_pk_bf16_f32 v13, v14, v15
	v_lshlrev_b32_e32 v14, 16, v18
	v_and_b32_e32 v15, 0xffff0000, v18
	v_lshlrev_b32_e32 v16, 16, v19
	v_and_b32_e32 v17, 0xffff0000, v19
	v_pk_fma_f32 v[14:15], v[14:15], s[18:19], v[90:91] op_sel_hi:[1,0,1]
	v_pk_fma_f32 v[16:17], v[16:17], s[18:19], v[82:83] op_sel_hi:[1,0,1]
	v_cvt_pk_bf16_f32 v14, v14, v15
	v_cvt_pk_bf16_f32 v15, v16, v17
	global_store_dwordx4 v[80:81], v[12:15], off offset:256
	s_waitcnt vmcnt(0)
; DI unsigned pk2(float lo, float hi) { f32x2 v = {lo, hi}; bf16x2v b = __builtin_convertvector(v, bf16x2v); return __builtin_bit_cast(unsigned, b); }
; DI float bflo(unsigned u) { return __uint_as_float(u << 16); }
; DI float bfhi(unsigned u) { return __uint_as_float(u & 0xffff0000u); }
;     __device__ __forceinline__ void operator()(const f32x4 (&acc)[2][2][4][2], const Unit& u, int wr, int wc, int fr, int fq) const {
;         const int row0 = u.pm * BM + wr * 64 + fr, col0 = u.pn * BM + wc * 32 + 8 * fq;
; #pragma unroll
;         for (int ai = 0; ai < 2; ++ai) {
;             int rowb = row0 + ai * HALF; asm volatile("" : "+v"(rowb)); const size_t off0 = (size_t)rowb * D + col0;
;             u32x4 xr[4][2];
; #pragma unroll
;             for (int m = 0; m < 4; ++m)
; #pragma unroll
;                 for (int bj = 0; bj < 2; ++bj) xr[m][bj] = *(const u32x4*)(XR + off0 + (size_t)(m * 16) * D + bj * HALF);
; #pragma unroll
;             for (int m = 0; m < 4; ++m)
; #pragma unroll
;                 for (int bj = 0; bj < 2; ++bj) { const u32x4 x = xr[m][bj]; const f32x4 v0 = acc[ai][bj][m][0] * (1.0f / 512.0f), v1 = acc[ai][bj][m][1] * (1.0f / 512.0f); u32x4 w;
;                     w.x = pk2(bflo(x.x) * ALPHA + v0[0], bfhi(x.x) * ALPHA + v0[1]); w.y = pk2(bflo(x.y) * ALPHA + v0[2], bfhi(x.y) * ALPHA + v0[3]);
;                     w.z = pk2(bflo(x.z) * ALPHA + v1[0], bfhi(x.z) * ALPHA + v1[1]); w.w = pk2(bflo(x.w) * ALPHA + v1[2], bfhi(x.w) * ALPHA + v1[3]);
;                     *(u32x4*)(H + off0 + (size_t)(m * 16) * D + bj * HALF) = w; }
;             asm volatile("" ::: "memory"); }
;     }
	v_lshlrev_b32_e32 v16, 16, v23
	v_lshlrev_b32_e32 v12, 16, v20
	v_and_b32_e32 v13, 0xffff0000, v20
	v_lshlrev_b32_e32 v14, 16, v21
	v_and_b32_e32 v15, 0xffff0000, v21
	v_pk_fma_f32 v[12:13], v[12:13], s[18:19], v[78:79] op_sel_hi:[1,0,1]
	v_pk_fma_f32 v[14:15], v[14:15], s[18:19], v[74:75] op_sel_hi:[1,0,1]
	v_cvt_pk_bf16_f32 v12, v12, v13
	v_cvt_pk_bf16_f32 v13, v14, v15
	v_lshlrev_b32_e32 v14, 16, v22
	v_and_b32_e32 v15, 0xffff0000, v22
	v_and_b32_e32 v17, 0xffff0000, v23
	v_pk_fma_f32 v[14:15], v[14:15], s[18:19], v[72:73] op_sel_hi:[1,0,1]
	v_pk_fma_f32 v[16:17], v[16:17], s[18:19], v[66:67] op_sel_hi:[1,0,1]
	v_cvt_pk_bf16_f32 v14, v14, v15
	v_cvt_pk_bf16_f32 v15, v16, v17
	v_add_co_u32_e32 v16, vcc, s94, v80
	v_lshlrev_b32_e32 v18, 16, v27
	s_nop 0
	v_addc_co_u32_e32 v17, vcc, 0, v81, vcc
	global_store_dwordx4 v[16:17], v[12:15], off
	v_and_b32_e32 v19, 0xffff0000, v27
	v_pk_fma_f32 v[18:19], v[18:19], s[18:19], v[64:65] op_sel_hi:[1,0,1]
	v_lshlrev_b32_e32 v12, 16, v24
	v_and_b32_e32 v13, 0xffff0000, v24
	v_lshlrev_b32_e32 v14, 16, v25
	v_and_b32_e32 v15, 0xffff0000, v25
	v_pk_fma_f32 v[12:13], v[12:13], s[18:19], v[76:77] op_sel_hi:[1,0,1]
	v_pk_fma_f32 v[14:15], v[14:15], s[18:19], v[68:69] op_sel_hi:[1,0,1]
	v_cvt_pk_bf16_f32 v12, v12, v13
	v_cvt_pk_bf16_f32 v13, v14, v15
	v_lshlrev_b32_e32 v14, 16, v26
	v_and_b32_e32 v15, 0xffff0000, v26
	v_pk_fma_f32 v[14:15], v[14:15], s[18:19], v[70:71] op_sel_hi:[1,0,1]
	s_nop 0
	v_cvt_pk_bf16_f32 v14, v14, v15
	v_cvt_pk_bf16_f32 v15, v18, v19
	global_store_dwordx4 v[16:17], v[12:15], off offset:256
	v_lshlrev_b32_e32 v16, 16, v47
	v_and_b32_e32 v17, 0xffff0000, v47
	v_lshlrev_b32_e32 v12, 16, v44
	v_and_b32_e32 v13, 0xffff0000, v44
	v_lshlrev_b32_e32 v14, 16, v45
	v_and_b32_e32 v15, 0xffff0000, v45
	v_pk_fma_f32 v[12:13], v[12:13], s[18:19], v[62:63] op_sel_hi:[1,0,1]
	v_pk_fma_f32 v[14:15], v[14:15], s[18:19], v[56:57] op_sel_hi:[1,0,1]
	v_cvt_pk_bf16_f32 v12, v12, v13
	v_cvt_pk_bf16_f32 v13, v14, v15
	v_lshlrev_b32_e32 v14, 16, v46
	v_and_b32_e32 v15, 0xffff0000, v46
	v_pk_fma_f32 v[14:15], v[14:15], s[18:19], v[58:59] op_sel_hi:[1,0,1]
	v_pk_fma_f32 v[16:17], v[16:17], s[18:19], v[50:51] op_sel_hi:[1,0,1]
	v_cvt_pk_bf16_f32 v14, v14, v15
	v_cvt_pk_bf16_f32 v15, v16, v17
	v_add_co_u32_e32 v16, vcc, s16, v80
	v_lshlrev_b32_e32 v18, 16, v99
	s_nop 0
	v_addc_co_u32_e32 v17, vcc, 0, v81, vcc
	global_store_dwordx4 v[16:17], v[12:15], off
	v_and_b32_e32 v19, 0xffff0000, v99
	v_pk_fma_f32 v[18:19], v[18:19], s[18:19], v[48:49] op_sel_hi:[1,0,1]
	v_lshlrev_b32_e32 v12, 16, v96
	v_and_b32_e32 v13, 0xffff0000, v96
	v_lshlrev_b32_e32 v14, 16, v97
	v_and_b32_e32 v15, 0xffff0000, v97
	v_pk_fma_f32 v[12:13], v[12:13], s[18:19], v[60:61] op_sel_hi:[1,0,1]
	v_pk_fma_f32 v[14:15], v[14:15], s[18:19], v[52:53] op_sel_hi:[1,0,1]
	v_cvt_pk_bf16_f32 v12, v12, v13
	v_cvt_pk_bf16_f32 v13, v14, v15
	v_lshlrev_b32_e32 v14, 16, v98
	v_and_b32_e32 v15, 0xffff0000, v98
	v_pk_fma_f32 v[14:15], v[14:15], s[18:19], v[54:55] op_sel_hi:[1,0,1]
	s_nop 0
	v_cvt_pk_bf16_f32 v14, v14, v15
	v_cvt_pk_bf16_f32 v15, v18, v19
	global_store_dwordx4 v[16:17], v[12:15], off offset:256
	s_nop 1
	v_lshlrev_b32_e32 v12, 16, v8
	v_and_b32_e32 v13, 0xffff0000, v8
	v_pk_fma_f32 v[12:13], v[12:13], s[18:19], v[42:43] op_sel_hi:[1,0,1]
	s_nop 0
	v_cvt_pk_bf16_f32 v8, v12, v13
	v_lshlrev_b32_e32 v12, 16, v9
	v_and_b32_e32 v13, 0xffff0000, v9
	v_pk_fma_f32 v[12:13], v[12:13], s[18:19], v[34:35] op_sel_hi:[1,0,1]
	s_nop 0
	v_cvt_pk_bf16_f32 v9, v12, v13
	v_lshlrev_b32_e32 v12, 16, v10
	v_and_b32_e32 v13, 0xffff0000, v10
	v_pk_fma_f32 v[12:13], v[12:13], s[18:19], v[38:39] op_sel_hi:[1,0,1]
	s_nop 0
	v_cvt_pk_bf16_f32 v10, v12, v13
	v_lshlrev_b32_e32 v12, 16, v11
	v_and_b32_e32 v13, 0xffff0000, v11
	v_pk_fma_f32 v[12:13], v[12:13], s[18:19], v[30:31] op_sel_hi:[1,0,1]
	s_nop 0
	v_cvt_pk_bf16_f32 v11, v12, v13
	v_add_co_u32_e32 v12, vcc, s17, v80
	s_mov_b64 s[16:17], s[6:7]
	s_nop 0
	v_addc_co_u32_e32 v13, vcc, 0, v81, vcc
	global_store_dwordx4 v[12:13], v[8:11], off
	s_and_b64 vcc, exec, s[4:5]
	s_nop 0
	v_lshlrev_b32_e32 v8, 16, v4
	v_and_b32_e32 v9, 0xffff0000, v4
	v_pk_fma_f32 v[8:9], v[8:9], s[18:19], v[40:41] op_sel_hi:[1,0,1]
	s_nop 0
	v_cvt_pk_bf16_f32 v4, v8, v9
	v_lshlrev_b32_e32 v8, 16, v5
	v_and_b32_e32 v9, 0xffff0000, v5
	v_pk_fma_f32 v[8:9], v[8:9], s[18:19], v[32:33] op_sel_hi:[1,0,1]
	s_nop 0
	v_cvt_pk_bf16_f32 v5, v8, v9
	v_lshlrev_b32_e32 v8, 16, v6
	v_and_b32_e32 v9, 0xffff0000, v6
	v_pk_fma_f32 v[8:9], v[8:9], s[18:19], v[36:37] op_sel_hi:[1,0,1]
	s_nop 0
	v_cvt_pk_bf16_f32 v6, v8, v9
	v_lshlrev_b32_e32 v8, 16, v7
	v_and_b32_e32 v9, 0xffff0000, v7
	v_pk_fma_f32 v[8:9], v[8:9], s[18:19], v[28:29] op_sel_hi:[1,0,1]
	s_mov_b64 s[18:19], s[8:9]
	v_cvt_pk_bf16_f32 v7, v8, v9
	global_store_dwordx4 v[12:13], v[4:7], off offset:256
	s_cbranch_vccnz .LBB0_1157

; DI float frcp(float x) { return __builtin_amdgcn_rcpf(x); }
; template <class Epi, class Sched>
; __device__ __forceinline__ void gemm_phase(LAS unsigned char* lds, const Gemm g, const Sched& S, const Epi& E) {
;     ...
;         if constexpr (Epi::FP8) asm volatile("s_nop 15\n\ts_nop 15\n\ts_nop 15" ::: "memory");
;     __device__ __forceinline__ void operator()(const f32x4 (&acc)[2][2][4][2], const Unit& u, int wr, int wc, int fr, int fq) const {
;         const int row0 = u.pm * BM + wr * 64 + fr, col0 = (u.pn & 15) * 128 + wc * 32 + 8 * fq;
; #pragma unroll
;         for (int ai = 0; ai < 2; ++ai)
; #pragma unroll
;             for (int m = 0; m < 4; ++m) { const f32x4 g0 = acc[ai][0][m][0], g1 = acc[ai][0][m][1], u0 = acc[ai][1][m][0], u1 = acc[ai][1][m][1];
;                 f32x4 h0, h1;
; #pragma unroll
;                 for (int j = 0; j < 4; ++j) { const float t0 = __builtin_amdgcn_exp2f(g0[j] * (-0.03125f * 1.44269504088896f)), t1 = __builtin_amdgcn_exp2f(g1[j] * (-0.03125f * 1.44269504088896f));
;                     h0[j] = g0[j] * u0[j] * frcp(__builtin_fmaf(t0, 1024.0f, 1024.0f)); h1[j] = g1[j] * u1[j] * frcp(__builtin_fmaf(t1, 1024.0f, 1024.0f)); }
;                 u32x2 w; w.x = pk4_fp8(h0[0], h0[1], h0[2], h0[3]); w.y = pk4_fp8(h1[0], h1[1], h1[2], h1[3]);
;                 int rowi = row0 + ai * HALF + m * 16; asm volatile("" : "+v"(rowi));
;                 *(u32x2*)(HID + (size_t)rowi * DE + col0) = w; asm volatile("" ::: "memory"); }
;     }
.LBB0_1521:
	v_and_b32_e32 v240, 16, v212
	v_lshlrev_b32_e32 v248, 11, v240
	v_lshrrev_b32_e32 v240, 1, v240
	v_sub_u32_e32 v248, v248, v240
	v_mov_b32_e32 v249, 0
	v_mul_f32_e32 v5, 0xbd38aa3b, v140
	v_exp_f32_e32 v5, v5
	v_mul_f32_e32 v6, 0xbd38aa3b, v136
	v_exp_f32_e32 v6, v6
	v_mul_f32_e32 v7, v144, v140
	v_fmamk_f32 v5, v5, 0x44800000, v215
	v_rcp_f32_e32 v5, v5
	v_fmamk_f32 v6, v6, 0x44800000, v215
	v_rcp_f32_e32 v6, v6
	v_mul_f32_e32 v9, v145, v141
	v_mul_f32_e32 v5, v7, v5
	v_mul_f32_e32 v7, v132, v136
	v_mul_f32_e32 v8, v7, v6
	v_mul_f32_e32 v6, 0xbd38aa3b, v141
	v_exp_f32_e32 v6, v6
	v_mul_f32_e32 v7, 0xbd38aa3b, v137
	v_exp_f32_e32 v7, v7
	v_mul_f32_e32 v10, 0xbd38aa3b, v142
	v_fmamk_f32 v6, v6, 0x44800000, v215
	v_rcp_f32_e32 v6, v6
	v_fmamk_f32 v7, v7, 0x44800000, v215
	v_rcp_f32_e32 v7, v7
	v_exp_f32_e32 v10, v10
	v_mul_f32_e32 v9, v9, v6
	v_mul_f32_e32 v6, v133, v137
	v_mul_f32_e32 v11, v6, v7
	v_mul_f32_e32 v7, 0xbd38aa3b, v138
	v_exp_f32_e32 v7, v7
	v_mul_f32_e32 v12, 0xbd38aa3b, v143
	v_exp_f32_e32 v12, v12
	v_fmamk_f32 v6, v10, 0x44800000, v215
	v_rcp_f32_e32 v6, v6
	v_fmamk_f32 v7, v7, 0x44800000, v215
	v_rcp_f32_e32 v7, v7
	v_mul_f32_e32 v13, 0xbd38aa3b, v139
	v_fmamk_f32 v12, v12, 0x44800000, v215
	v_rcp_f32_e32 v12, v12
	v_exp_f32_e32 v13, v13
	v_mul_f32_e32 v10, v146, v142
	v_mul_f32_e32 v10, v10, v6
	v_mul_f32_e32 v6, v134, v138
	v_mov_b32_e32 v2, v1
	v_mul_f32_e32 v14, v6, v7
	v_mul_f32_e32 v6, v147, v143
	s_nop 15
	s_nop 15
	v_mul_f32_e32 v12, v6, v12
	v_readfirstlane_b32 s20, v2
	v_fmamk_f32 v6, v13, 0x44800000, v215
	s_ashr_i32 s22, s20, 2
	v_rcp_f32_e32 v13, v6
	v_mov_b32_e32 v6, v3
	v_mov_b32_e32 v7, v3
	s_lshl_b32 s21, s57, 8
	s_andn2_b32 s22, s22, 63
	v_cvt_pk_fp8_f32 v6, v5, v9
	v_cvt_pk_fp8_f32 v7, v8, v11
	s_add_i32 s22, s22, s21
	v_and_or_b32 v4, v2, 15, s22
	v_mul_f32_e32 v5, v135, v139
	s_lshl_b32 s21, s56, 7
	v_mul_f32_e32 v5, v5, v13
	v_mov_b32_e32 v8, v4
	s_and_b32 s21, s21, 0x780
	s_lshr_b32 s20, s20, 1
	v_lshrrev_b32_e32 v2, 1, v2
	v_cvt_pk_fp8_f32 v6, v10, v12 op_sel:[0,0,1]
	v_cvt_pk_fp8_f32 v7, v14, v5 op_sel:[0,0,1]
	s_and_b32 s20, s20, 0x60
	v_ashrrev_i32_e32 v9, 31, v8
	v_and_or_b32 v2, v2, 24, s21
	v_lshlrev_b64 v[8:9], 11, v[8:9]
	v_or_b32_e32 v2, s20, v2
	v_lshl_add_u64 v[8:9], s[10:11], 0, v[8:9]
	v_lshl_add_u64 v[8:9], v[8:9], 0, v[2:3]
	v_mul_f32_e32 v5, 0xbd38aa3b, v128
	v_mov_b32_e32 v242, v6
	v_mov_b32_e32 v243, v7
	v_mov_b32_e32 v246, v8
	v_mov_b32_e32 v247, v9
	v_exp_f32_e32 v5, v5
	v_mul_f32_e32 v6, 0xbd38aa3b, v120
	v_exp_f32_e32 v6, v6
	v_mul_f32_e32 v7, v124, v128
	v_fmamk_f32 v5, v5, 0x44800000, v215
	v_rcp_f32_e32 v5, v5
	v_fmamk_f32 v6, v6, 0x44800000, v215
	v_rcp_f32_e32 v6, v6
	v_mul_f32_e32 v9, v125, v129
	v_mul_f32_e32 v5, v7, v5
	v_mul_f32_e32 v7, v116, v120
	v_mul_f32_e32 v8, v7, v6
	v_mul_f32_e32 v6, 0xbd38aa3b, v129
	v_exp_f32_e32 v6, v6
	v_mul_f32_e32 v7, 0xbd38aa3b, v121
	v_exp_f32_e32 v7, v7
	v_mul_f32_e32 v10, 0xbd38aa3b, v130
	v_fmamk_f32 v6, v6, 0x44800000, v215
	v_rcp_f32_e32 v6, v6
	v_fmamk_f32 v7, v7, 0x44800000, v215
	v_rcp_f32_e32 v7, v7
	v_exp_f32_e32 v10, v10
	v_mul_f32_e32 v9, v9, v6
	v_mul_f32_e32 v6, v117, v121
	v_mul_f32_e32 v11, v6, v7
	v_mul_f32_e32 v7, 0xbd38aa3b, v122
	v_exp_f32_e32 v7, v7
	v_mul_f32_e32 v12, 0xbd38aa3b, v131
	v_exp_f32_e32 v12, v12
	v_fmamk_f32 v6, v10, 0x44800000, v215
	v_rcp_f32_e32 v6, v6
	v_fmamk_f32 v7, v7, 0x44800000, v215
	v_rcp_f32_e32 v7, v7
	v_mul_f32_e32 v13, 0xbd38aa3b, v123
	v_fmamk_f32 v12, v12, 0x44800000, v215
	v_rcp_f32_e32 v12, v12
	v_exp_f32_e32 v13, v13
	v_mul_f32_e32 v10, v126, v130
	v_mul_f32_e32 v10, v10, v6
	v_mul_f32_e32 v6, v118, v122
	v_mul_f32_e32 v14, v6, v7
	v_mul_f32_e32 v6, v127, v131
	v_mul_f32_e32 v12, v6, v12
	v_fmamk_f32 v6, v13, 0x44800000, v215
	v_rcp_f32_e32 v13, v6
	v_mov_b32_e32 v6, v3
	v_mov_b32_e32 v7, v3
	v_cvt_pk_fp8_f32 v6, v5, v9
	v_cvt_pk_fp8_f32 v7, v8, v11
	v_mul_f32_e32 v5, v119, v123
	v_mul_f32_e32 v5, v5, v13
	v_or_b32_e32 v8, 16, v4
	v_cvt_pk_fp8_f32 v6, v10, v12 op_sel:[0,0,1]
	v_cvt_pk_fp8_f32 v7, v14, v5 op_sel:[0,0,1]
	v_mul_f32_e32 v5, 0xbd38aa3b, v112
	v_ashrrev_i32_e32 v9, 31, v8
	v_lshlrev_b64 v[8:9], 11, v[8:9]
	v_lshl_add_u64 v[8:9], s[10:11], 0, v[8:9]
	v_lshl_add_u64 v[8:9], v[8:9], 0, v[2:3]
	v_mov_b32_e32 v244, v6
	v_mov_b32_e32 v245, v7
	v_lshl_add_u64 v[246:247], v[246:247], 0, v[248:249]
	s_nop 0
	v_permlane16_swap_b32_e32 v242, v244
	v_permlane16_swap_b32_e32 v243, v245
	global_store_dwordx4 v[246:247], v[242:245], off
	v_exp_f32_e32 v5, v5
	v_mul_f32_e32 v6, 0xbd38aa3b, v104
	v_exp_f32_e32 v6, v6
	v_mul_f32_e32 v7, v108, v112
	v_fmamk_f32 v5, v5, 0x44800000, v215
	v_rcp_f32_e32 v5, v5
	v_fmamk_f32 v6, v6, 0x44800000, v215
	v_rcp_f32_e32 v6, v6
	v_mul_f32_e32 v9, v109, v113
	v_mul_f32_e32 v5, v7, v5
	v_mul_f32_e32 v7, v100, v104
	v_mul_f32_e32 v8, v7, v6
	v_mul_f32_e32 v6, 0xbd38aa3b, v113
	v_exp_f32_e32 v6, v6
	v_mul_f32_e32 v7, 0xbd38aa3b, v105
	v_exp_f32_e32 v7, v7
	v_mul_f32_e32 v10, 0xbd38aa3b, v114
	v_fmamk_f32 v6, v6, 0x44800000, v215
	v_rcp_f32_e32 v6, v6
	v_fmamk_f32 v7, v7, 0x44800000, v215
	v_rcp_f32_e32 v7, v7
	v_exp_f32_e32 v10, v10
	v_mul_f32_e32 v9, v9, v6
	v_mul_f32_e32 v6, v101, v105
	v_mul_f32_e32 v11, v6, v7
	v_mul_f32_e32 v7, 0xbd38aa3b, v106
	v_exp_f32_e32 v7, v7
	v_mul_f32_e32 v12, 0xbd38aa3b, v115
	v_exp_f32_e32 v12, v12
	v_fmamk_f32 v6, v10, 0x44800000, v215
	v_rcp_f32_e32 v6, v6
	v_fmamk_f32 v7, v7, 0x44800000, v215
	v_rcp_f32_e32 v7, v7
	v_mul_f32_e32 v13, 0xbd38aa3b, v107
	v_fmamk_f32 v12, v12, 0x44800000, v215
	v_rcp_f32_e32 v12, v12
	v_exp_f32_e32 v13, v13
	v_mul_f32_e32 v10, v110, v114
	v_mul_f32_e32 v10, v10, v6
; DI float frcp(float x) { return __builtin_amdgcn_rcpf(x); }
;     __device__ __forceinline__ void operator()(const f32x4 (&acc)[2][2][4][2], const Unit& u, int wr, int wc, int fr, int fq) const {
;     ...
;             for (int m = 0; m < 4; ++m) { const f32x4 g0 = acc[ai][0][m][0], g1 = acc[ai][0][m][1], u0 = acc[ai][1][m][0], u1 = acc[ai][1][m][1];
;                 f32x4 h0, h1;
; #pragma unroll
;                 for (int j = 0; j < 4; ++j) { const float t0 = __builtin_amdgcn_exp2f(g0[j] * (-0.03125f * 1.44269504088896f)), t1 = __builtin_amdgcn_exp2f(g1[j] * (-0.03125f * 1.44269504088896f));
;                     h0[j] = g0[j] * u0[j] * frcp(__builtin_fmaf(t0, 1024.0f, 1024.0f)); h1[j] = g1[j] * u1[j] * frcp(__builtin_fmaf(t1, 1024.0f, 1024.0f)); }
;                 u32x2 w; w.x = pk4_fp8(h0[0], h0[1], h0[2], h0[3]); w.y = pk4_fp8(h1[0], h1[1], h1[2], h1[3]);
;                 int rowi = row0 + ai * HALF + m * 16; asm volatile("" : "+v"(rowi));
;                 *(u32x2*)(HID + (size_t)rowi * DE + col0) = w; asm volatile("" ::: "memory"); }
	v_mul_f32_e32 v6, v102, v106
	v_mul_f32_e32 v14, v6, v7
	v_mul_f32_e32 v6, v111, v115
	v_mul_f32_e32 v12, v6, v12
	v_fmamk_f32 v6, v13, 0x44800000, v215
	v_rcp_f32_e32 v13, v6
	v_mov_b32_e32 v6, v3
	v_mov_b32_e32 v7, v3
	v_cvt_pk_fp8_f32 v6, v5, v9
	v_cvt_pk_fp8_f32 v7, v8, v11
	v_mul_f32_e32 v5, v103, v107
	v_mul_f32_e32 v5, v5, v13
	v_or_b32_e32 v8, 32, v4
	v_cvt_pk_fp8_f32 v6, v10, v12 op_sel:[0,0,1]
	v_cvt_pk_fp8_f32 v7, v14, v5 op_sel:[0,0,1]
	v_mul_f32_e32 v5, 0xbd38aa3b, v96
	v_ashrrev_i32_e32 v9, 31, v8
	v_lshlrev_b64 v[8:9], 11, v[8:9]
	v_lshl_add_u64 v[8:9], s[10:11], 0, v[8:9]
	v_lshl_add_u64 v[8:9], v[8:9], 0, v[2:3]
	v_mov_b32_e32 v242, v6
	v_mov_b32_e32 v243, v7
	v_mov_b32_e32 v246, v8
	v_mov_b32_e32 v247, v9
	v_exp_f32_e32 v5, v5
	v_mul_f32_e32 v6, 0xbd38aa3b, v88
	v_exp_f32_e32 v6, v6
	v_mul_f32_e32 v7, v92, v96
	v_fmamk_f32 v5, v5, 0x44800000, v215
	v_rcp_f32_e32 v5, v5
	v_fmamk_f32 v6, v6, 0x44800000, v215
	v_rcp_f32_e32 v6, v6
	v_mul_f32_e32 v9, v93, v97
	v_mul_f32_e32 v5, v7, v5
	v_mul_f32_e32 v7, v84, v88
	v_mul_f32_e32 v8, v7, v6
	v_mul_f32_e32 v6, 0xbd38aa3b, v97
	v_exp_f32_e32 v6, v6
	v_mul_f32_e32 v7, 0xbd38aa3b, v89
	v_exp_f32_e32 v7, v7
	v_mul_f32_e32 v10, 0xbd38aa3b, v98
	v_fmamk_f32 v6, v6, 0x44800000, v215
	v_rcp_f32_e32 v6, v6
	v_fmamk_f32 v7, v7, 0x44800000, v215
	v_rcp_f32_e32 v7, v7
	v_exp_f32_e32 v10, v10
	v_mul_f32_e32 v9, v9, v6
	v_mul_f32_e32 v6, v85, v89
	v_mul_f32_e32 v11, v6, v7
	v_mul_f32_e32 v7, 0xbd38aa3b, v90
	v_exp_f32_e32 v7, v7
	v_mul_f32_e32 v12, 0xbd38aa3b, v99
	v_exp_f32_e32 v12, v12
	v_fmamk_f32 v6, v10, 0x44800000, v215
	v_rcp_f32_e32 v6, v6
	v_fmamk_f32 v7, v7, 0x44800000, v215
	v_rcp_f32_e32 v7, v7
	v_mul_f32_e32 v13, 0xbd38aa3b, v91
	v_fmamk_f32 v12, v12, 0x44800000, v215
	v_rcp_f32_e32 v12, v12
	v_exp_f32_e32 v13, v13
	v_mul_f32_e32 v10, v94, v98
	v_mul_f32_e32 v10, v10, v6
	v_mul_f32_e32 v6, v86, v90
	v_mul_f32_e32 v14, v6, v7
	v_mul_f32_e32 v6, v95, v99
	v_mul_f32_e32 v12, v6, v12
	v_fmamk_f32 v6, v13, 0x44800000, v215
	v_rcp_f32_e32 v13, v6
	v_mov_b32_e32 v6, v3
	v_mov_b32_e32 v7, v3
	v_cvt_pk_fp8_f32 v6, v5, v9
	v_cvt_pk_fp8_f32 v7, v8, v11
	v_mul_f32_e32 v5, v87, v91
	v_mul_f32_e32 v5, v5, v13
	v_or_b32_e32 v8, 48, v4
	v_cvt_pk_fp8_f32 v6, v10, v12 op_sel:[0,0,1]
	v_cvt_pk_fp8_f32 v7, v14, v5 op_sel:[0,0,1]
	v_mul_f32_e32 v5, 0xbd38aa3b, v80
	v_ashrrev_i32_e32 v9, 31, v8
	v_lshlrev_b64 v[8:9], 11, v[8:9]
	v_lshl_add_u64 v[8:9], s[10:11], 0, v[8:9]
	v_lshl_add_u64 v[8:9], v[8:9], 0, v[2:3]
	v_mov_b32_e32 v244, v6
	v_mov_b32_e32 v245, v7
	v_lshl_add_u64 v[246:247], v[246:247], 0, v[248:249]
	s_nop 0
	v_permlane16_swap_b32_e32 v242, v244
	v_permlane16_swap_b32_e32 v243, v245
	global_store_dwordx4 v[246:247], v[242:245], off
	v_exp_f32_e32 v5, v5
	v_mul_f32_e32 v6, 0xbd38aa3b, v72
	v_exp_f32_e32 v7, v6
	v_mul_f32_e32 v8, v76, v80
	v_fmamk_f32 v5, v5, 0x44800000, v215
	v_rcp_f32_e32 v5, v5
	v_fmamk_f32 v7, v7, 0x44800000, v215
	v_rcp_f32_e32 v7, v7
	v_mul_f32_e32 v9, 0xbd38aa3b, v73
	v_mul_f32_e32 v5, v8, v5
	v_mul_f32_e32 v8, v68, v72
	v_mul_f32_e32 v7, v8, v7
	v_mul_f32_e32 v8, 0xbd38aa3b, v81
	v_exp_f32_e32 v8, v8
	v_exp_f32_e32 v9, v9
	v_mul_f32_e32 v10, v77, v81
	v_mul_f32_e32 v11, 0xbd38aa3b, v82
	v_fmamk_f32 v8, v8, 0x44800000, v215
	v_rcp_f32_e32 v8, v8
	v_fmamk_f32 v9, v9, 0x44800000, v215
	v_rcp_f32_e32 v9, v9
	v_exp_f32_e32 v11, v11
	v_mul_f32_e32 v10, v10, v8
	v_mul_f32_e32 v8, v69, v73
	v_mul_f32_e32 v12, v8, v9
	v_mul_f32_e32 v9, 0xbd38aa3b, v74
	v_exp_f32_e32 v9, v9
	v_mul_f32_e32 v13, 0xbd38aa3b, v83
	v_exp_f32_e32 v13, v13
	v_fmamk_f32 v8, v11, 0x44800000, v215
	v_rcp_f32_e32 v8, v8
	v_fmamk_f32 v9, v9, 0x44800000, v215
	v_rcp_f32_e32 v9, v9
	v_mul_f32_e32 v14, 0xbd38aa3b, v75
	v_fmamk_f32 v13, v13, 0x44800000, v215
	v_rcp_f32_e32 v13, v13
	v_exp_f32_e32 v14, v14
	v_mul_f32_e32 v11, v78, v82
	v_mul_f32_e32 v11, v11, v8
	v_mul_f32_e32 v8, v70, v74
	v_mul_f32_e32 v15, v8, v9
	v_mul_f32_e32 v8, v79, v83
	v_mul_f32_e32 v13, v8, v13
	v_fmamk_f32 v8, v14, 0x44800000, v215
	v_rcp_f32_e32 v14, v8
	v_mov_b32_e32 v8, v3
	v_mov_b32_e32 v9, v3
	v_cvt_pk_fp8_f32 v8, v5, v10
	v_cvt_pk_fp8_f32 v9, v7, v12
	v_mul_f32_e32 v5, v71, v75
	v_add_u32_e32 v6, 0x80, v4
	v_mul_f32_e32 v5, v5, v14
	v_cvt_pk_fp8_f32 v8, v11, v13 op_sel:[0,0,1]
	v_cvt_pk_fp8_f32 v9, v15, v5 op_sel:[0,0,1]
	v_mul_f32_e32 v5, 0xbd38aa3b, v64
	v_ashrrev_i32_e32 v7, 31, v6
	v_lshlrev_b64 v[6:7], 11, v[6:7]
	v_lshl_add_u64 v[6:7], s[10:11], 0, v[6:7]
	v_lshl_add_u64 v[6:7], v[6:7], 0, v[2:3]
	v_mov_b32_e32 v242, v8
	v_mov_b32_e32 v243, v9
	v_mov_b32_e32 v246, v6
	v_mov_b32_e32 v247, v7
	v_exp_f32_e32 v5, v5
	v_mul_f32_e32 v6, 0xbd38aa3b, v56
	v_exp_f32_e32 v6, v6
	v_mul_f32_e32 v7, v60, v64
	v_fmamk_f32 v5, v5, 0x44800000, v215
	v_rcp_f32_e32 v5, v5
	v_fmamk_f32 v6, v6, 0x44800000, v215
	v_rcp_f32_e32 v6, v6
	v_mul_f32_e32 v9, v61, v65
	v_mul_f32_e32 v5, v7, v5
	v_mul_f32_e32 v7, v52, v56
	v_mul_f32_e32 v8, v7, v6
	v_mul_f32_e32 v6, 0xbd38aa3b, v65
	v_exp_f32_e32 v6, v6
	v_mul_f32_e32 v7, 0xbd38aa3b, v57
	v_exp_f32_e32 v7, v7
	v_mul_f32_e32 v10, 0xbd38aa3b, v66
	v_fmamk_f32 v6, v6, 0x44800000, v215
	v_rcp_f32_e32 v6, v6
	v_fmamk_f32 v7, v7, 0x44800000, v215
	v_rcp_f32_e32 v7, v7
	v_exp_f32_e32 v10, v10
	v_mul_f32_e32 v9, v9, v6
	v_mul_f32_e32 v6, v53, v57
	v_mul_f32_e32 v11, v6, v7
; DI float frcp(float x) { return __builtin_amdgcn_rcpf(x); }
; template <class Epi, class Sched>
; __device__ __forceinline__ void gemm_phase(LAS unsigned char* lds, const Gemm g, const Sched& S, const Epi& E) {
;     ...
;           E(acc, cur, wz >> 2, wz & 3, lz & 15, lz >> 4); } S.done(cur);
;         if (!has_next) break;
; #pragma unroll
;         for (int a = 0; a < 2; ++a)
; #pragma unroll
;             for (int b = 0; b < 2; ++b)
; #pragma unroll
;                 for (int m = 0; m < 4; ++m)
; #pragma unroll
;                     for (int n = 0; n < 2; ++n) acc[a][b][m][n] = (f32x4){0.f, 0.f, 0.f, 0.f};
;         cur = nxt; cA = nA; cB = nB; ++ui;
;     __device__ __forceinline__ void operator()(const f32x4 (&acc)[2][2][4][2], const Unit& u, int wr, int wc, int fr, int fq) const {
;     ...
;             for (int m = 0; m < 4; ++m) { const f32x4 g0 = acc[ai][0][m][0], g1 = acc[ai][0][m][1], u0 = acc[ai][1][m][0], u1 = acc[ai][1][m][1];
;                 f32x4 h0, h1;
; #pragma unroll
;                 for (int j = 0; j < 4; ++j) { const float t0 = __builtin_amdgcn_exp2f(g0[j] * (-0.03125f * 1.44269504088896f)), t1 = __builtin_amdgcn_exp2f(g1[j] * (-0.03125f * 1.44269504088896f));
;                     h0[j] = g0[j] * u0[j] * frcp(__builtin_fmaf(t0, 1024.0f, 1024.0f)); h1[j] = g1[j] * u1[j] * frcp(__builtin_fmaf(t1, 1024.0f, 1024.0f)); }
;                 u32x2 w; w.x = pk4_fp8(h0[0], h0[1], h0[2], h0[3]); w.y = pk4_fp8(h1[0], h1[1], h1[2], h1[3]);
;                 int rowi = row0 + ai * HALF + m * 16; asm volatile("" : "+v"(rowi));
;                 *(u32x2*)(HID + (size_t)rowi * DE + col0) = w; asm volatile("" ::: "memory"); }
;     }
	v_mul_f32_e32 v7, 0xbd38aa3b, v58
	v_exp_f32_e32 v7, v7
	v_mul_f32_e32 v12, 0xbd38aa3b, v67
	v_exp_f32_e32 v12, v12
	v_fmamk_f32 v6, v10, 0x44800000, v215
	v_rcp_f32_e32 v6, v6
	v_fmamk_f32 v7, v7, 0x44800000, v215
	v_rcp_f32_e32 v7, v7
	v_mul_f32_e32 v13, 0xbd38aa3b, v59
	v_fmamk_f32 v12, v12, 0x44800000, v215
	v_rcp_f32_e32 v12, v12
	v_exp_f32_e32 v13, v13
	v_mul_f32_e32 v10, v62, v66
	v_mul_f32_e32 v10, v10, v6
	v_mul_f32_e32 v6, v54, v58
	v_mul_f32_e32 v14, v6, v7
	v_mul_f32_e32 v6, v63, v67
	v_mul_f32_e32 v12, v6, v12
	v_fmamk_f32 v6, v13, 0x44800000, v215
	v_rcp_f32_e32 v13, v6
	v_mov_b32_e32 v6, v3
	v_mov_b32_e32 v7, v3
	v_cvt_pk_fp8_f32 v6, v5, v9
	v_cvt_pk_fp8_f32 v7, v8, v11
	v_mul_f32_e32 v5, v55, v59
	v_mul_f32_e32 v5, v5, v13
	v_add_u32_e32 v8, 0x90, v4
	v_cvt_pk_fp8_f32 v6, v10, v12 op_sel:[0,0,1]
	v_cvt_pk_fp8_f32 v7, v14, v5 op_sel:[0,0,1]
	v_mul_f32_e32 v5, 0xbd38aa3b, v48
	v_ashrrev_i32_e32 v9, 31, v8
	v_lshlrev_b64 v[8:9], 11, v[8:9]
	v_lshl_add_u64 v[8:9], s[10:11], 0, v[8:9]
	v_lshl_add_u64 v[8:9], v[8:9], 0, v[2:3]
	v_mov_b32_e32 v244, v6
	v_mov_b32_e32 v245, v7
	v_lshl_add_u64 v[246:247], v[246:247], 0, v[248:249]
	s_nop 0
	v_permlane16_swap_b32_e32 v242, v244
	v_permlane16_swap_b32_e32 v243, v245
	global_store_dwordx4 v[246:247], v[242:245], off
	v_exp_f32_e32 v5, v5
	v_mul_f32_e32 v6, 0xbd38aa3b, v40
	v_exp_f32_e32 v6, v6
	v_mul_f32_e32 v7, v44, v48
	v_fmamk_f32 v5, v5, 0x44800000, v215
	v_rcp_f32_e32 v5, v5
	v_fmamk_f32 v6, v6, 0x44800000, v215
	v_rcp_f32_e32 v6, v6
	v_mul_f32_e32 v9, v45, v49
	v_mul_f32_e32 v5, v7, v5
	v_mul_f32_e32 v7, v36, v40
	v_mul_f32_e32 v8, v7, v6
	v_mul_f32_e32 v6, 0xbd38aa3b, v49
	v_exp_f32_e32 v6, v6
	v_mul_f32_e32 v7, 0xbd38aa3b, v41
	v_exp_f32_e32 v7, v7
	v_mul_f32_e32 v10, 0xbd38aa3b, v50
	v_fmamk_f32 v6, v6, 0x44800000, v215
	v_rcp_f32_e32 v6, v6
	v_fmamk_f32 v7, v7, 0x44800000, v215
	v_rcp_f32_e32 v7, v7
	v_exp_f32_e32 v10, v10
	v_mul_f32_e32 v9, v9, v6
	v_mul_f32_e32 v6, v37, v41
	v_mul_f32_e32 v11, v6, v7
	v_mul_f32_e32 v7, 0xbd38aa3b, v42
	v_exp_f32_e32 v7, v7
	v_mul_f32_e32 v12, 0xbd38aa3b, v51
	v_exp_f32_e32 v12, v12
	v_fmamk_f32 v6, v10, 0x44800000, v215
	v_rcp_f32_e32 v6, v6
	v_fmamk_f32 v7, v7, 0x44800000, v215
	v_rcp_f32_e32 v7, v7
	v_mul_f32_e32 v13, 0xbd38aa3b, v43
	v_fmamk_f32 v12, v12, 0x44800000, v215
	v_rcp_f32_e32 v12, v12
	v_exp_f32_e32 v13, v13
	v_mul_f32_e32 v10, v46, v50
	v_mul_f32_e32 v10, v10, v6
	v_mul_f32_e32 v6, v38, v42
	v_mul_f32_e32 v14, v6, v7
	v_mul_f32_e32 v6, v47, v51
	v_mul_f32_e32 v12, v6, v12
	v_fmamk_f32 v6, v13, 0x44800000, v215
	v_rcp_f32_e32 v13, v6
	v_mov_b32_e32 v6, v3
	v_mov_b32_e32 v7, v3
	v_cvt_pk_fp8_f32 v6, v5, v9
	v_cvt_pk_fp8_f32 v7, v8, v11
	v_mul_f32_e32 v5, v39, v43
	v_mul_f32_e32 v5, v5, v13
	v_add_u32_e32 v8, 0xa0, v4
	v_cvt_pk_fp8_f32 v6, v10, v12 op_sel:[0,0,1]
	v_cvt_pk_fp8_f32 v7, v14, v5 op_sel:[0,0,1]
	v_mul_f32_e32 v5, 0xbd38aa3b, v32
	v_ashrrev_i32_e32 v9, 31, v8
	v_lshlrev_b64 v[8:9], 11, v[8:9]
	v_lshl_add_u64 v[8:9], s[10:11], 0, v[8:9]
	v_lshl_add_u64 v[8:9], v[8:9], 0, v[2:3]
	v_mov_b32_e32 v242, v6
	v_mov_b32_e32 v243, v7
	v_mov_b32_e32 v246, v8
	v_mov_b32_e32 v247, v9
	v_exp_f32_e32 v5, v5
	v_mul_f32_e32 v6, 0xbd38aa3b, v24
	v_exp_f32_e32 v6, v6
	v_mul_f32_e32 v7, v28, v32
	v_fmamk_f32 v5, v5, 0x44800000, v215
	v_rcp_f32_e32 v5, v5
	v_fmamk_f32 v6, v6, 0x44800000, v215
	v_rcp_f32_e32 v6, v6
	v_mul_f32_e32 v9, v29, v33
	v_mul_f32_e32 v5, v7, v5
	v_mul_f32_e32 v7, v20, v24
	v_mul_f32_e32 v8, v7, v6
	v_mul_f32_e32 v6, 0xbd38aa3b, v33
	v_exp_f32_e32 v6, v6
	v_mul_f32_e32 v7, 0xbd38aa3b, v25
	v_exp_f32_e32 v7, v7
	v_mul_f32_e32 v10, 0xbd38aa3b, v34
	v_fmamk_f32 v6, v6, 0x44800000, v215
	v_rcp_f32_e32 v6, v6
	v_fmamk_f32 v7, v7, 0x44800000, v215
	v_rcp_f32_e32 v7, v7
	v_exp_f32_e32 v10, v10
	v_mul_f32_e32 v9, v9, v6
	v_mul_f32_e32 v6, v21, v25
	v_mul_f32_e32 v11, v6, v7
	v_mul_f32_e32 v7, 0xbd38aa3b, v26
	v_exp_f32_e32 v7, v7
	v_mul_f32_e32 v12, 0xbd38aa3b, v35
	v_exp_f32_e32 v12, v12
	v_fmamk_f32 v6, v10, 0x44800000, v215
	v_rcp_f32_e32 v6, v6
	v_fmamk_f32 v7, v7, 0x44800000, v215
	v_rcp_f32_e32 v7, v7
	v_mul_f32_e32 v13, 0xbd38aa3b, v27
	v_fmamk_f32 v12, v12, 0x44800000, v215
	v_rcp_f32_e32 v12, v12
	v_exp_f32_e32 v13, v13
	v_mul_f32_e32 v10, v30, v34
	v_mul_f32_e32 v10, v10, v6
	v_mul_f32_e32 v6, v22, v26
	v_mul_f32_e32 v14, v6, v7
	v_mul_f32_e32 v6, v31, v35
	v_mul_f32_e32 v12, v6, v12
	v_fmamk_f32 v6, v13, 0x44800000, v215
	v_rcp_f32_e32 v13, v6
	v_mov_b32_e32 v6, v3
	v_mov_b32_e32 v7, v3
	v_cvt_pk_fp8_f32 v6, v5, v9
	v_cvt_pk_fp8_f32 v7, v8, v11
	v_mul_f32_e32 v5, v23, v27
	v_mul_f32_e32 v5, v5, v13
	v_add_u32_e32 v4, 0xb0, v4
	v_cvt_pk_fp8_f32 v6, v10, v12 op_sel:[0,0,1]
	v_cvt_pk_fp8_f32 v7, v14, v5 op_sel:[0,0,1]
	s_and_b64 vcc, exec, s[14:15]
	v_ashrrev_i32_e32 v5, 31, v4
	v_lshlrev_b64 v[4:5], 11, v[4:5]
	v_lshl_add_u64 v[4:5], s[10:11], 0, v[4:5]
	v_lshl_add_u64 v[4:5], v[4:5], 0, v[2:3]
	v_mov_b32_e32 v244, v6
	v_mov_b32_e32 v245, v7
	v_lshl_add_u64 v[246:247], v[246:247], 0, v[248:249]
	s_nop 0
	v_permlane16_swap_b32_e32 v242, v244
	v_permlane16_swap_b32_e32 v243, v245
	global_store_dwordx4 v[246:247], v[242:245], off
	s_mov_b32 s56, s55
	s_mov_b32 s57, s54
	s_mov_b32 s25, s55
	s_mov_b32 s24, s54
	s_mov_b64 s[22:23], s[18:19]
	s_mov_b64 s[20:21], s[16:17]
	s_cbranch_vccnz .LBB0_1538

; DI unsigned pk2(float lo, float hi) { f32x2 v = {lo, hi}; bf16x2v b = __builtin_convertvector(v, bf16x2v); return __builtin_bit_cast(unsigned, b); }
; template <class Epi, class Sched>
; __device__ __forceinline__ void gemm_phase(LAS unsigned char* lds, const Gemm g, const Sched& S, const Epi& E) {
;     ...
;         if constexpr (Epi::FP8) asm volatile("s_nop 15\n\ts_nop 15\n\ts_nop 15" ::: "memory");
;     __device__ __forceinline__ void operator()(const f32x4 (&acc)[2][2][4][2], const Unit& u, int wr, int wc, int fr, int fq) const {
;         const int row0 = u.pm * BM + wr * 64 + fr, col0 = (u.pn & 3) * BM + wc * 32 + 8 * fq;
;         float gvs[2][4];
; #pragma unroll
;         for (int ai = 0; ai < 2; ++ai)
; #pragma unroll
;             for (int m = 0; m < 4; ++m) gvs[ai][m] = GV[row0 + ai * HALF + m * 16];
; #pragma unroll
;         for (int ai = 0; ai < 2; ++ai)
; #pragma unroll
;             for (int m = 0; m < 4; ++m) { int row = row0 + ai * HALF + m * 16; asm volatile("" : "+v"(row)); const float gv = gvs[ai][m] * 0.03125f;
; #pragma unroll
;                 for (int bj = 0; bj < 2; ++bj) { const f32x4 v0 = acc[ai][bj][m][0] * gv, v1 = acc[ai][bj][m][1] * gv;
;                     u32x4 w; w.x = pk2(v0[0], v0[1]); w.y = pk2(v0[2], v0[3]); w.z = pk2(v1[0], v1[1]); w.w = pk2(v1[2], v1[3]);
;                     *(u32x4*)(Y + (size_t)row * D + col0 + bj * HALF) = w; } }
.LBB0_1601:
	v_mov_b32_e32 v2, v1
	s_nop 15
	s_nop 15
	s_lshl_b32 s21, s55, 8
	v_readfirstlane_b32 s20, v2
	s_ashr_i32 s22, s20, 2
	s_andn2_b32 s22, s22, 63
	s_add_i32 s22, s22, s21
	v_and_or_b32 v18, v2, 15, s22
	v_ashrrev_i32_e32 v19, 31, v18
	v_lshl_add_u64 v[160:161], v[18:19], 2, s[10:11]
	global_load_dword v15, v[160:161], off
	global_load_dword v17, v[160:161], off offset:64
	global_load_dword v162, v[160:161], off offset:128
	global_load_dword v13, v[160:161], off offset:192
	global_load_dword v11, v[160:161], off offset:512
	global_load_dword v9, v[160:161], off offset:576
	global_load_dword v7, v[160:161], off offset:640
	global_load_dword v5, v[160:161], off offset:704
	s_lshl_b32 s21, s54, 8
	s_lshr_b32 s20, s20, 1
	v_lshrrev_b32_e32 v2, 1, v2
	s_and_b32 s21, s21, 0x300
	s_and_b32 s20, s20, 0x60
	v_or_b32_e32 v16, 16, v18
	v_or_b32_e32 v14, 32, v18
	v_or_b32_e32 v12, 48, v18
	v_add_u32_e32 v10, 0x80, v18
	v_add_u32_e32 v8, 0x90, v18
	v_add_u32_e32 v6, 0xa0, v18
	v_add_u32_e32 v4, 0xb0, v18
	v_and_or_b32 v2, v2, 24, s21
	v_or_b32_e32 v2, s20, v2
	v_ashrrev_i32_e32 v19, 31, v18
	v_lshlrev_b64 v[18:19], 11, v[18:19]
	v_lshl_add_u64 v[18:19], s[0:1], 0, v[18:19]
	v_lshlrev_b32_e32 v2, 1, v2
	v_lshl_add_u64 v[18:19], v[18:19], 0, v[2:3]
	s_and_b64 vcc, exec, s[14:15]
	s_mov_b32 s54, s53
	s_mov_b32 s55, s52
	s_mov_b32 s25, s53
	s_mov_b32 s24, s52
	s_mov_b64 s[22:23], s[18:19]
	s_mov_b64 s[20:21], s[16:17]
	s_waitcnt vmcnt(0)
	v_mul_f32_e32 v160, 0x3d000000, v15
	v_pk_mul_f32 v[142:143], v[142:143], v[160:161] op_sel_hi:[1,0]
	v_pk_mul_f32 v[140:141], v[140:141], v[160:161] op_sel_hi:[1,0]
	v_pk_mul_f32 v[146:147], v[146:147], v[160:161] op_sel_hi:[1,0]
	v_pk_mul_f32 v[144:145], v[144:145], v[160:161] op_sel_hi:[1,0]
	v_cvt_pk_bf16_f32 v140, v140, v141
	v_cvt_pk_bf16_f32 v141, v142, v143
	v_cvt_pk_bf16_f32 v142, v144, v145
	v_cvt_pk_bf16_f32 v143, v146, v147
	global_store_dwordx4 v[18:19], v[140:143], off
	v_pk_mul_f32 v[138:139], v[138:139], v[160:161] op_sel_hi:[1,0]
	v_pk_mul_f32 v[136:137], v[136:137], v[160:161] op_sel_hi:[1,0]
	v_pk_mul_f32 v[140:141], v[134:135], v[160:161] op_sel_hi:[1,0]
	v_pk_mul_f32 v[134:135], v[132:133], v[160:161] op_sel_hi:[1,0]
	v_cvt_pk_bf16_f32 v132, v136, v137
	v_cvt_pk_bf16_f32 v133, v138, v139
	v_cvt_pk_bf16_f32 v134, v134, v135
	v_cvt_pk_bf16_f32 v135, v140, v141
	global_store_dwordx4 v[18:19], v[132:135], off offset:256
	s_nop 1
	v_mul_f32_e32 v132, 0x3d000000, v17
	v_ashrrev_i32_e32 v17, 31, v16
	v_lshlrev_b64 v[134:135], 11, v[16:17]
	v_pk_mul_f32 v[18:19], v[130:131], v[132:133] op_sel_hi:[1,0]
	v_pk_mul_f32 v[16:17], v[128:129], v[132:133] op_sel_hi:[1,0]
	v_pk_mul_f32 v[124:125], v[124:125], v[132:133] op_sel_hi:[1,0]
	v_pk_mul_f32 v[126:127], v[126:127], v[132:133] op_sel_hi:[1,0]
	v_cvt_pk_bf16_f32 v16, v16, v17
	v_cvt_pk_bf16_f32 v17, v18, v19
	v_cvt_pk_bf16_f32 v18, v124, v125
	v_lshl_add_u64 v[124:125], s[0:1], 0, v[134:135]
	v_cvt_pk_bf16_f32 v19, v126, v127
	v_lshl_add_u64 v[124:125], v[124:125], 0, v[2:3]
	global_store_dwordx4 v[124:125], v[16:19], off
	v_pk_mul_f32 v[118:119], v[118:119], v[132:133] op_sel_hi:[1,0]
	v_pk_mul_f32 v[116:117], v[116:117], v[132:133] op_sel_hi:[1,0]
	v_pk_mul_f32 v[18:19], v[122:123], v[132:133] op_sel_hi:[1,0]
	v_pk_mul_f32 v[16:17], v[120:121], v[132:133] op_sel_hi:[1,0]
	s_nop 0
	v_cvt_pk_bf16_f32 v16, v16, v17
	v_cvt_pk_bf16_f32 v17, v18, v19
	v_cvt_pk_bf16_f32 v18, v116, v117
	v_cvt_pk_bf16_f32 v19, v118, v119
	global_store_dwordx4 v[124:125], v[16:19], off offset:256
	s_nop 0
	v_ashrrev_i32_e32 v15, 31, v14
	v_mul_f32_e32 v18, 0x3d000000, v162
	v_lshlrev_b64 v[116:117], 11, v[14:15]
	v_pk_mul_f32 v[16:17], v[114:115], v[18:19] op_sel_hi:[1,0]
	v_pk_mul_f32 v[14:15], v[112:113], v[18:19] op_sel_hi:[1,0]
	v_pk_mul_f32 v[108:109], v[108:109], v[18:19] op_sel_hi:[1,0]
	v_pk_mul_f32 v[110:111], v[110:111], v[18:19] op_sel_hi:[1,0]
	v_cvt_pk_bf16_f32 v14, v14, v15
	v_cvt_pk_bf16_f32 v15, v16, v17
	v_cvt_pk_bf16_f32 v16, v108, v109
	v_lshl_add_u64 v[108:109], s[0:1], 0, v[116:117]
	v_cvt_pk_bf16_f32 v17, v110, v111
	v_lshl_add_u64 v[108:109], v[108:109], 0, v[2:3]
	global_store_dwordx4 v[108:109], v[14:17], off
	v_pk_mul_f32 v[102:103], v[102:103], v[18:19] op_sel_hi:[1,0]
	s_nop 0
	v_pk_mul_f32 v[16:17], v[106:107], v[18:19] op_sel_hi:[1,0]
	v_pk_mul_f32 v[14:15], v[104:105], v[18:19] op_sel_hi:[1,0]
	v_pk_mul_f32 v[18:19], v[100:101], v[18:19] op_sel_hi:[1,0]
	v_cvt_pk_bf16_f32 v14, v14, v15
	v_cvt_pk_bf16_f32 v15, v16, v17
	v_cvt_pk_bf16_f32 v16, v18, v19
	v_cvt_pk_bf16_f32 v17, v102, v103
	global_store_dwordx4 v[108:109], v[14:17], off offset:256
	s_nop 1
	v_mul_f32_e32 v16, 0x3d000000, v13
	v_ashrrev_i32_e32 v13, 31, v12
	v_lshlrev_b64 v[18:19], 11, v[12:13]
	v_pk_mul_f32 v[14:15], v[98:99], v[16:17] op_sel_hi:[1,0]
	v_pk_mul_f32 v[12:13], v[96:97], v[16:17] op_sel_hi:[1,0]
	v_pk_mul_f32 v[94:95], v[94:95], v[16:17] op_sel_hi:[1,0]
; DI unsigned pk2(float lo, float hi) { f32x2 v = {lo, hi}; bf16x2v b = __builtin_convertvector(v, bf16x2v); return __builtin_bit_cast(unsigned, b); }
;     __device__ __forceinline__ void operator()(const f32x4 (&acc)[2][2][4][2], const Unit& u, int wr, int wc, int fr, int fq) const {
;     ...
;             for (int m = 0; m < 4; ++m) { int row = row0 + ai * HALF + m * 16; asm volatile("" : "+v"(row)); const float gv = gvs[ai][m] * 0.03125f;
; #pragma unroll
;                 for (int bj = 0; bj < 2; ++bj) { const f32x4 v0 = acc[ai][bj][m][0] * gv, v1 = acc[ai][bj][m][1] * gv;
;                     u32x4 w; w.x = pk2(v0[0], v0[1]); w.y = pk2(v0[2], v0[3]); w.z = pk2(v1[0], v1[1]); w.w = pk2(v1[2], v1[3]);
;                     *(u32x4*)(Y + (size_t)row * D + col0 + bj * HALF) = w; } }
	v_pk_mul_f32 v[92:93], v[92:93], v[16:17] op_sel_hi:[1,0]
	v_lshl_add_u64 v[18:19], s[0:1], 0, v[18:19]
	v_cvt_pk_bf16_f32 v12, v12, v13
	v_cvt_pk_bf16_f32 v13, v14, v15
	v_cvt_pk_bf16_f32 v14, v92, v93
	v_cvt_pk_bf16_f32 v15, v94, v95
	v_lshl_add_u64 v[18:19], v[18:19], 0, v[2:3]
	global_store_dwordx4 v[18:19], v[12:15], off
	v_pk_mul_f32 v[86:87], v[86:87], v[16:17] op_sel_hi:[1,0]
	s_nop 0
	v_pk_mul_f32 v[14:15], v[90:91], v[16:17] op_sel_hi:[1,0]
	v_pk_mul_f32 v[12:13], v[88:89], v[16:17] op_sel_hi:[1,0]
	v_pk_mul_f32 v[16:17], v[84:85], v[16:17] op_sel_hi:[1,0]
	v_cvt_pk_bf16_f32 v12, v12, v13
	v_cvt_pk_bf16_f32 v13, v14, v15
	v_cvt_pk_bf16_f32 v14, v16, v17
	v_cvt_pk_bf16_f32 v15, v86, v87
	global_store_dwordx4 v[18:19], v[12:15], off offset:256
	s_nop 1
	v_mul_f32_e32 v14, 0x3d000000, v11
	v_ashrrev_i32_e32 v11, 31, v10
	v_lshlrev_b64 v[16:17], 11, v[10:11]
	v_pk_mul_f32 v[12:13], v[82:83], v[14:15] op_sel_hi:[1,0]
	v_pk_mul_f32 v[10:11], v[80:81], v[14:15] op_sel_hi:[1,0]
	v_pk_mul_f32 v[18:19], v[78:79], v[14:15] op_sel_hi:[1,0]
	v_pk_mul_f32 v[76:77], v[76:77], v[14:15] op_sel_hi:[1,0]
	v_lshl_add_u64 v[16:17], s[0:1], 0, v[16:17]
	v_cvt_pk_bf16_f32 v10, v10, v11
	v_cvt_pk_bf16_f32 v11, v12, v13
	v_cvt_pk_bf16_f32 v12, v76, v77
	v_cvt_pk_bf16_f32 v13, v18, v19
	v_lshl_add_u64 v[16:17], v[16:17], 0, v[2:3]
	global_store_dwordx4 v[16:17], v[10:13], off
	v_pk_mul_f32 v[18:19], v[70:71], v[14:15] op_sel_hi:[1,0]
	s_nop 0
	v_pk_mul_f32 v[12:13], v[74:75], v[14:15] op_sel_hi:[1,0]
	v_pk_mul_f32 v[10:11], v[72:73], v[14:15] op_sel_hi:[1,0]
	v_pk_mul_f32 v[14:15], v[68:69], v[14:15] op_sel_hi:[1,0]
	v_cvt_pk_bf16_f32 v10, v10, v11
	v_cvt_pk_bf16_f32 v11, v12, v13
	v_cvt_pk_bf16_f32 v12, v14, v15
	v_cvt_pk_bf16_f32 v13, v18, v19
	global_store_dwordx4 v[16:17], v[10:13], off offset:256
	s_nop 1
	v_mul_f32_e32 v12, 0x3d000000, v9
	v_ashrrev_i32_e32 v9, 31, v8
	v_lshlrev_b64 v[14:15], 11, v[8:9]
	v_pk_mul_f32 v[10:11], v[66:67], v[12:13] op_sel_hi:[1,0]
	v_pk_mul_f32 v[8:9], v[64:65], v[12:13] op_sel_hi:[1,0]
	v_pk_mul_f32 v[16:17], v[62:63], v[12:13] op_sel_hi:[1,0]
	v_pk_mul_f32 v[18:19], v[60:61], v[12:13] op_sel_hi:[1,0]
	v_lshl_add_u64 v[14:15], s[0:1], 0, v[14:15]
	v_cvt_pk_bf16_f32 v8, v8, v9
	v_cvt_pk_bf16_f32 v9, v10, v11
	v_cvt_pk_bf16_f32 v10, v18, v19
	v_cvt_pk_bf16_f32 v11, v16, v17
	v_lshl_add_u64 v[14:15], v[14:15], 0, v[2:3]
	global_store_dwordx4 v[14:15], v[8:11], off
	v_pk_mul_f32 v[16:17], v[54:55], v[12:13] op_sel_hi:[1,0]
	s_nop 0
	v_pk_mul_f32 v[10:11], v[58:59], v[12:13] op_sel_hi:[1,0]
	v_pk_mul_f32 v[8:9], v[56:57], v[12:13] op_sel_hi:[1,0]
	v_pk_mul_f32 v[12:13], v[52:53], v[12:13] op_sel_hi:[1,0]
	v_cvt_pk_bf16_f32 v8, v8, v9
	v_cvt_pk_bf16_f32 v9, v10, v11
	v_cvt_pk_bf16_f32 v10, v12, v13
	v_cvt_pk_bf16_f32 v11, v16, v17
	global_store_dwordx4 v[14:15], v[8:11], off offset:256
	s_nop 1
	v_mul_f32_e32 v10, 0x3d000000, v7
	v_ashrrev_i32_e32 v7, 31, v6
	v_lshlrev_b64 v[12:13], 11, v[6:7]
	v_pk_mul_f32 v[8:9], v[50:51], v[10:11] op_sel_hi:[1,0]
	v_pk_mul_f32 v[6:7], v[48:49], v[10:11] op_sel_hi:[1,0]
	v_pk_mul_f32 v[14:15], v[46:47], v[10:11] op_sel_hi:[1,0]
	v_pk_mul_f32 v[16:17], v[44:45], v[10:11] op_sel_hi:[1,0]
	v_lshl_add_u64 v[12:13], s[0:1], 0, v[12:13]
	v_cvt_pk_bf16_f32 v6, v6, v7
	v_cvt_pk_bf16_f32 v7, v8, v9
	v_cvt_pk_bf16_f32 v8, v16, v17
	v_cvt_pk_bf16_f32 v9, v14, v15
	v_lshl_add_u64 v[12:13], v[12:13], 0, v[2:3]
	global_store_dwordx4 v[12:13], v[6:9], off
	v_pk_mul_f32 v[14:15], v[38:39], v[10:11] op_sel_hi:[1,0]
	s_nop 0
	v_pk_mul_f32 v[8:9], v[42:43], v[10:11] op_sel_hi:[1,0]
	v_pk_mul_f32 v[6:7], v[40:41], v[10:11] op_sel_hi:[1,0]
	v_pk_mul_f32 v[10:11], v[36:37], v[10:11] op_sel_hi:[1,0]
	v_cvt_pk_bf16_f32 v6, v6, v7
	v_cvt_pk_bf16_f32 v7, v8, v9
	v_cvt_pk_bf16_f32 v8, v10, v11
	v_cvt_pk_bf16_f32 v9, v14, v15
	global_store_dwordx4 v[12:13], v[6:9], off offset:256
	s_nop 1
	v_mul_f32_e32 v8, 0x3d000000, v5
	v_ashrrev_i32_e32 v5, 31, v4
	v_lshlrev_b64 v[10:11], 11, v[4:5]
	v_pk_mul_f32 v[6:7], v[34:35], v[8:9] op_sel_hi:[1,0]
	v_pk_mul_f32 v[4:5], v[32:33], v[8:9] op_sel_hi:[1,0]
	v_pk_mul_f32 v[12:13], v[30:31], v[8:9] op_sel_hi:[1,0]
	v_pk_mul_f32 v[14:15], v[28:29], v[8:9] op_sel_hi:[1,0]
	v_lshl_add_u64 v[10:11], s[0:1], 0, v[10:11]
	v_cvt_pk_bf16_f32 v4, v4, v5
	v_cvt_pk_bf16_f32 v5, v6, v7
	v_cvt_pk_bf16_f32 v6, v14, v15
	v_cvt_pk_bf16_f32 v7, v12, v13
	v_lshl_add_u64 v[10:11], v[10:11], 0, v[2:3]
	global_store_dwordx4 v[10:11], v[4:7], off
	v_pk_mul_f32 v[12:13], v[22:23], v[8:9] op_sel_hi:[1,0]
	s_nop 0
	v_pk_mul_f32 v[6:7], v[26:27], v[8:9] op_sel_hi:[1,0]
	v_pk_mul_f32 v[4:5], v[24:25], v[8:9] op_sel_hi:[1,0]
	v_pk_mul_f32 v[8:9], v[20:21], v[8:9] op_sel_hi:[1,0]
	v_cvt_pk_bf16_f32 v4, v4, v5
	v_cvt_pk_bf16_f32 v5, v6, v7
	v_cvt_pk_bf16_f32 v6, v8, v9
	v_cvt_pk_bf16_f32 v7, v12, v13
	global_store_dwordx4 v[10:11], v[4:7], off offset:256
	s_cbranch_vccnz .LBB0_1618
